# cross-attention K tile LDS row stride 528 to 544 bytes: conflict-free ds_read_b128 fragments
# baseline (speedup 1.0000x reference)
; __device__ __forceinline__ u32x4 pack8(const float* f) { u32x4 o; o.x = pk2(f[0], f[1]); o.y = pk2(f[2], f[3]); o.z = pk2(f[4], f[5]); o.w = pk2(f[6], f[7]); return o; }
; __device__ __forceinline__ void phase_xattn(CArgs& A, int l, unsigned char* lds, int tid) {
;     ...
;         const int wave = tid >> 6, lane = tid & 63, r = lane & 15, g = lane >> 4;
;         const int b = it >> 6, h = (it >> 4) & 3, qch = it & 15;
;         const size_t row = (size_t)b * SEQ + qch * 128 + wave * 16 + r;
;         bf16x8 qf[8];
; #pragma unroll
;         for (int ks = 0; ks < 8; ++ks) { float f[8]; unpack8(*(const u32x4*)(Q + row * DM + h * 256 + 32 * ks + 8 * g), f);
; #pragma unroll
;             for (int i = 0; i < 8; ++i) f[i] *= 0.0625f;
;             qf[ks] = __builtin_bit_cast(bf16x8, pack8(f)); }
;         f32x4 o[16];
; #pragma unroll
;         for (int i = 0; i < 16; ++i) o[i] = (f32x4){0.f, 0.f, 0.f, 0.f};
;         float m = -INFINITY, lsum = 0.f;
;         const int skey = tid >> 3, sdc = (tid & 7) * 32;
;         const bf16* kvbase = KV + ((size_t)b * NMEM + skey) * 4096 + l * 2048 + h * 256 + sdc;
;         u32x4 kr[4], vr[4];
; #pragma unroll
;         for (int i = 0; i < 4; ++i) { kr[i] = *(const u32x4*)(kvbase + i * 8); vr[i] = *(const u32x4*)(kvbase + 1024 + i * 8); }
.LBB0_144:
	s_ashr_i32 s4, s11, 6
	s_ashr_i32 s5, s4, 31
	s_lshl_b32 s8, s11, 7
	s_lshl_b64 s[0:1], s[4:5], 11
	s_and_b32 s8, s8, 0x780
	v_ashrrev_i32_e32 v2, 2, v1
	v_and_b32_e32 v36, 15, v1
	s_or_b32 s0, s0, s8
	v_and_b32_e32 v2, -16, v2
	v_ashrrev_i32_e32 v3, 31, v2
	v_or_b32_e32 v4, s0, v36
	v_mov_b32_e32 v5, s1
	v_lshl_add_u64 v[2:3], v[4:5], 0, v[2:3]
	s_lshl_b32 s0, s11, 4
	v_lshlrev_b64 v[144:145], 11, v[2:3]
	s_and_b32 s36, s0, 0x300
	v_bfe_u32 v37, v1, 4, 2
	v_lshl_add_u64 v[2:3], s[38:39], 0, v[144:145]
	s_lshl_b32 s14, s36, 1
	v_lshl_add_u64 v[2:3], v[2:3], 0, s[14:15]
	v_lshlrev_b32_e32 v34, 4, v37
	v_mov_b32_e32 v35, v0
	v_lshl_add_u64 v[22:23], v[2:3], 0, v[34:35]
	global_load_dwordx4 v[2:5], v[22:23], off
	global_load_dwordx4 v[6:9], v[22:23], off offset:64
	global_load_dwordx4 v[10:13], v[22:23], off offset:128
	global_load_dwordx4 v[14:17], v[22:23], off offset:192
	global_load_dwordx4 v[18:21], v[22:23], off offset:256
	s_mov_b32 s0, 0x3d800000
	v_mov_b32_e32 v147, v0
	v_cmp_lt_i32_e32 vcc, v178, v173
	v_lshlrev_b32_e32 v143, 2, v37
	v_and_b32_e32 v37, 7, v1
	v_lshlrev_b32_e32 v37, 6, v37
	v_mul_u32_u24_e32 v36, 0x220, v36
	v_mov_b32_e32 v130, 0
	v_mov_b32_e32 v156, 0xff800000
	s_mov_b64 s[44:45], 0
	v_mov_b32_e32 v51, v130
	s_waitcnt lgkmcnt(0)
	v_mov_b32_e32 v52, v130
	s_waitcnt lgkmcnt(2)
	v_mov_b32_e32 v53, v130
	v_mov_b32_e32 v54, 0
	v_mov_b32_e32 v55, v130
	s_waitcnt lgkmcnt(1)
	v_mov_b32_e32 v56, v130
	s_waitcnt lgkmcnt(0)
	v_mov_b32_e32 v57, v130
	v_mov_b32_e32 v58, 0
	v_mov_b32_e32 v59, v130
	v_mov_b32_e32 v60, v130
	v_mov_b32_e32 v61, v130
	v_mov_b32_e32 v74, 0
	v_mov_b32_e32 v75, v130
	v_mov_b32_e32 v76, v130
	v_mov_b32_e32 v77, v130
	s_waitcnt vmcnt(0)
	v_mov_b32_e32 v94, 0
	v_mov_b32_e32 v95, v130
	v_mov_b32_e32 v96, v130
	v_mov_b32_e32 v97, v130
	v_mov_b32_e32 v82, 0
	v_mov_b32_e32 v83, v130
	v_mov_b32_e32 v84, v130
	v_mov_b32_e32 v85, v130
	v_mov_b32_e32 v90, 0
	v_mov_b32_e32 v91, v130
	v_mov_b32_e32 v92, v130
	v_mov_b32_e32 v93, v130
	v_mov_b32_e32 v78, 0
	v_mov_b32_e32 v79, v130
	v_mov_b32_e32 v80, v130
	v_mov_b32_e32 v81, v130
	v_mov_b32_e32 v70, 0
	v_mov_b32_e32 v71, v130
	v_mov_b32_e32 v72, v130
	v_mov_b32_e32 v73, v130
	v_mov_b32_e32 v62, 0
	v_mov_b32_e32 v63, v130
	v_mov_b32_e32 v64, v130
	v_mov_b32_e32 v65, v130
	v_mov_b32_e32 v66, 0
	v_mov_b32_e32 v67, v130
	v_mov_b32_e32 v68, v130
	v_mov_b32_e32 v69, v130
	v_mov_b32_e32 v86, 0
	v_mov_b32_e32 v87, v130
	v_mov_b32_e32 v88, v130
	v_mov_b32_e32 v89, v130
	s_waitcnt vmcnt(4)
	v_lshlrev_b32_e32 v25, 16, v3
	v_lshlrev_b32_e32 v24, 16, v2
	v_and_b32_e32 v3, 0xffff0000, v3
	v_and_b32_e32 v2, 0xffff0000, v2
	v_lshlrev_b32_e32 v27, 16, v5
	v_lshlrev_b32_e32 v26, 16, v4
	v_and_b32_e32 v5, 0xffff0000, v5
	v_and_b32_e32 v4, 0xffff0000, v4
	s_waitcnt vmcnt(3)
	v_lshlrev_b32_e32 v29, 16, v7
	v_lshlrev_b32_e32 v28, 16, v6
	v_and_b32_e32 v7, 0xffff0000, v7
	v_and_b32_e32 v6, 0xffff0000, v6
	v_lshlrev_b32_e32 v31, 16, v9
	v_lshlrev_b32_e32 v30, 16, v8
	v_and_b32_e32 v9, 0xffff0000, v9
	v_and_b32_e32 v8, 0xffff0000, v8
	v_pk_mul_f32 v[24:25], v[24:25], s[0:1] op_sel_hi:[1,0]
	v_pk_mul_f32 v[2:3], v[2:3], s[0:1] op_sel_hi:[1,0]
	v_pk_mul_f32 v[26:27], v[26:27], s[0:1] op_sel_hi:[1,0]
	v_pk_mul_f32 v[4:5], v[4:5], s[0:1] op_sel_hi:[1,0]
	v_pk_mul_f32 v[28:29], v[28:29], s[0:1] op_sel_hi:[1,0]
	v_pk_mul_f32 v[6:7], v[6:7], s[0:1] op_sel_hi:[1,0]
	v_pk_mul_f32 v[30:31], v[30:31], s[0:1] op_sel_hi:[1,0]
	v_pk_mul_f32 v[8:9], v[8:9], s[0:1] op_sel_hi:[1,0]
	v_bfe_u32 v39, v24, 16, 1
	v_bfe_u32 v32, v5, 16, 1
	v_bfe_u32 v35, v3, 16, 1
	v_bfe_u32 v38, v2, 16, 1
	v_bfe_u32 v40, v25, 16, 1
	v_bfe_u32 v41, v26, 16, 1
	v_bfe_u32 v42, v27, 16, 1
	v_bfe_u32 v44, v8, 16, 1
	v_bfe_u32 v46, v6, 16, 1
	v_bfe_u32 v47, v28, 16, 1
	v_bfe_u32 v49, v30, 16, 1
	v_bfe_u32 v50, v31, 16, 1
	v_add3_u32 v24, v24, v39, s84
	v_bfe_u32 v33, v4, 16, 1
	v_bfe_u32 v43, v9, 16, 1
	v_bfe_u32 v45, v7, 16, 1
	v_bfe_u32 v48, v29, 16, 1
	v_add3_u32 v2, v2, v38, s84
	v_add3_u32 v3, v3, v35, s84
	v_add3_u32 v5, v5, v32, s84
	v_add3_u32 v27, v27, v42, s84
	v_add3_u32 v26, v26, v41, s84
	v_add3_u32 v25, v25, v40, s84
	v_add3_u32 v32, v6, v46, s84
	v_add3_u32 v35, v8, v44, s84
	v_add3_u32 v31, v31, v50, s84
	v_add3_u32 v6, v30, v49, s84
	v_add3_u32 v8, v28, v47, s84
	v_lshrrev_b32_e32 v24, 16, v24
	v_add3_u32 v4, v4, v33, s84
	v_add3_u32 v33, v7, v45, s84
	v_add3_u32 v38, v9, v43, s84
	v_add3_u32 v7, v29, v48, s84
	v_lshrrev_b32_e32 v25, 16, v25
	v_lshrrev_b32_e32 v26, 16, v26
	v_lshrrev_b32_e32 v9, 16, v27
	v_lshrrev_b32_e32 v27, 16, v8
	v_lshrrev_b32_e32 v29, 16, v6
	v_and_or_b32 v6, v2, s3, v24
	v_lshrrev_b32_e32 v2, 16, v31
	v_lshrrev_b32_e32 v28, 16, v7
	v_and_or_b32 v9, v5, s3, v9
	v_and_or_b32 v8, v4, s3, v26
	v_and_or_b32 v7, v3, s3, v25
	v_and_or_b32 v5, v38, s3, v2
	v_and_or_b32 v2, v32, s3, v27
	s_waitcnt vmcnt(2)
	v_lshlrev_b32_e32 v25, 16, v11
	v_lshlrev_b32_e32 v24, 16, v10
	v_and_b32_e32 v11, 0xffff0000, v11
	v_and_b32_e32 v10, 0xffff0000, v10
	v_lshlrev_b32_e32 v27, 16, v13
	v_lshlrev_b32_e32 v26, 16, v12
	v_and_b32_e32 v13, 0xffff0000, v13
	v_and_b32_e32 v12, 0xffff0000, v12
	v_pk_mul_f32 v[10:11], v[10:11], s[0:1] op_sel_hi:[1,0]
	v_pk_mul_f32 v[12:13], v[12:13], s[0:1] op_sel_hi:[1,0]
	v_and_or_b32 v4, v35, s3, v29
	v_and_or_b32 v3, v33, s3, v28
	v_pk_mul_f32 v[24:25], v[24:25], s[0:1] op_sel_hi:[1,0]
	v_pk_mul_f32 v[26:27], v[26:27], s[0:1] op_sel_hi:[1,0]
	v_bfe_u32 v28, v13, 16, 1
	v_bfe_u32 v29, v12, 16, 1
	v_bfe_u32 v30, v11, 16, 1
	v_bfe_u32 v31, v10, 16, 1
	v_add3_u32 v10, v10, v31, s84
	v_add3_u32 v11, v11, v30, s84
	v_add3_u32 v12, v12, v29, s84
	v_add3_u32 v13, v13, v28, s84
	v_bfe_u32 v28, v24, 16, 1
	v_bfe_u32 v29, v25, 16, 1
	v_bfe_u32 v30, v26, 16, 1
	v_bfe_u32 v31, v27, 16, 1
	v_add3_u32 v31, v27, v31, s84
	v_add3_u32 v26, v26, v30, s84
	v_add3_u32 v25, v25, v29, s84
	v_add3_u32 v24, v24, v28, s84
	v_lshrrev_b32_e32 v28, 16, v24
	v_lshrrev_b32_e32 v29, 16, v25
	v_lshrrev_b32_e32 v30, 16, v26
	global_load_dwordx4 v[24:27], v[22:23], off offset:320
	v_lshrrev_b32_e32 v31, 16, v31
	v_and_or_b32 v13, v13, s3, v31
	v_and_or_b32 v12, v12, s3, v30
	s_waitcnt vmcnt(2)
; __device__ __forceinline__ u32x4 pack8(const float* f) { u32x4 o; o.x = pk2(f[0], f[1]); o.y = pk2(f[2], f[3]); o.z = pk2(f[4], f[5]); o.w = pk2(f[6], f[7]); return o; }
; __device__ __forceinline__ void phase_xattn(CArgs& A, int l, unsigned char* lds, int tid) {
;     ...
;         for (int ks = 0; ks < 8; ++ks) { float f[8]; unpack8(*(const u32x4*)(Q + row * DM + h * 256 + 32 * ks + 8 * g), f);
; #pragma unroll
;             for (int i = 0; i < 8; ++i) f[i] *= 0.0625f;
;             qf[ks] = __builtin_bit_cast(bf16x8, pack8(f)); }
	v_lshlrev_b32_e32 v31, 16, v17
	v_lshlrev_b32_e32 v30, 16, v16
	v_and_b32_e32 v17, 0xffff0000, v17
	v_and_b32_e32 v16, 0xffff0000, v16
	v_and_or_b32 v11, v11, s3, v29
	v_and_or_b32 v10, v10, s3, v28
	v_lshlrev_b32_e32 v29, 16, v15
	v_lshlrev_b32_e32 v28, 16, v14
	v_and_b32_e32 v15, 0xffff0000, v15
	v_and_b32_e32 v14, 0xffff0000, v14
	v_pk_mul_f32 v[16:17], v[16:17], s[0:1] op_sel_hi:[1,0]
	v_pk_mul_f32 v[28:29], v[28:29], s[0:1] op_sel_hi:[1,0]
	v_pk_mul_f32 v[14:15], v[14:15], s[0:1] op_sel_hi:[1,0]
	v_bfe_u32 v32, v17, 16, 1
	v_bfe_u32 v33, v16, 16, 1
	v_pk_mul_f32 v[30:31], v[30:31], s[0:1] op_sel_hi:[1,0]
	v_bfe_u32 v35, v15, 16, 1
	v_bfe_u32 v38, v14, 16, 1
	v_add3_u32 v16, v16, v33, s84
	v_add3_u32 v17, v17, v32, s84
	v_bfe_u32 v32, v28, 16, 1
	v_bfe_u32 v33, v29, 16, 1
	v_add3_u32 v14, v14, v38, s84
	v_add3_u32 v15, v15, v35, s84
	v_bfe_u32 v35, v30, 16, 1
	v_bfe_u32 v38, v31, 16, 1
	v_add3_u32 v29, v29, v33, s84
	v_add3_u32 v28, v28, v32, s84
	v_add3_u32 v38, v31, v38, s84
	v_add3_u32 v35, v30, v35, s84
	v_lshrrev_b32_e32 v32, 16, v28
	v_lshrrev_b32_e32 v33, 16, v29
	global_load_dwordx4 v[28:31], v[22:23], off offset:384
	v_lshrrev_b32_e32 v38, 16, v38
	v_and_or_b32 v17, v17, s3, v38
	v_and_or_b32 v15, v15, s3, v33
	v_and_or_b32 v14, v14, s3, v32
	s_waitcnt vmcnt(2)
	v_lshlrev_b32_e32 v33, 16, v19
	v_lshlrev_b32_e32 v32, 16, v18
	v_and_b32_e32 v19, 0xffff0000, v19
	v_and_b32_e32 v18, 0xffff0000, v18
	v_lshlrev_b32_e32 v39, 16, v21
	v_lshlrev_b32_e32 v38, 16, v20
	v_and_b32_e32 v21, 0xffff0000, v21
	v_and_b32_e32 v20, 0xffff0000, v20
	v_pk_mul_f32 v[18:19], v[18:19], s[0:1] op_sel_hi:[1,0]
	v_pk_mul_f32 v[20:21], v[20:21], s[0:1] op_sel_hi:[1,0]
	v_pk_mul_f32 v[32:33], v[32:33], s[0:1] op_sel_hi:[1,0]
	v_pk_mul_f32 v[38:39], v[38:39], s[0:1] op_sel_hi:[1,0]
	v_bfe_u32 v40, v20, 16, 1
	v_bfe_u32 v41, v19, 16, 1
	v_bfe_u32 v42, v18, 16, 1
	v_add3_u32 v18, v18, v42, s84
	v_add3_u32 v19, v19, v41, s84
	v_add3_u32 v20, v20, v40, s84
	v_bfe_u32 v40, v33, 16, 1
	v_bfe_u32 v41, v38, 16, 1
	v_bfe_u32 v42, v39, 16, 1
	v_add3_u32 v42, v39, v42, s84
	v_add3_u32 v43, v38, v41, s84
	v_add3_u32 v33, v33, v40, s84
	global_load_dwordx4 v[38:41], v[22:23], off offset:448
	v_lshrrev_b32_e32 v35, 16, v35
	v_and_or_b32 v16, v16, s3, v35
	v_bfe_u32 v35, v21, 16, 1
	v_add3_u32 v21, v21, v35, s84
	v_bfe_u32 v35, v32, 16, 1
	v_add3_u32 v32, v32, v35, s84
	v_lshrrev_b32_e32 v32, 16, v32
	v_lshrrev_b32_e32 v22, 16, v33
	v_lshrrev_b32_e32 v23, 16, v43
	v_lshrrev_b32_e32 v33, 16, v42
	v_and_or_b32 v21, v21, s3, v33
	v_and_or_b32 v20, v20, s3, v23
	v_and_or_b32 v19, v19, s3, v22
	v_and_or_b32 v18, v18, s3, v32
	s_waitcnt vmcnt(2)
	v_lshlrev_b32_e32 v23, 16, v25
	v_lshlrev_b32_e32 v22, 16, v24
	v_and_b32_e32 v25, 0xffff0000, v25
	v_and_b32_e32 v24, 0xffff0000, v24
	v_lshlrev_b32_e32 v33, 16, v27
	v_lshlrev_b32_e32 v32, 16, v26
	v_and_b32_e32 v27, 0xffff0000, v27
	v_and_b32_e32 v26, 0xffff0000, v26
	v_pk_mul_f32 v[24:25], v[24:25], s[0:1] op_sel_hi:[1,0]
	v_pk_mul_f32 v[26:27], v[26:27], s[0:1] op_sel_hi:[1,0]
	v_pk_mul_f32 v[32:33], v[32:33], s[0:1] op_sel_hi:[1,0]
	v_bfe_u32 v35, v27, 16, 1
	v_bfe_u32 v42, v26, 16, 1
	v_bfe_u32 v43, v25, 16, 1
	v_bfe_u32 v44, v24, 16, 1
	v_pk_mul_f32 v[22:23], v[22:23], s[0:1] op_sel_hi:[1,0]
	v_add3_u32 v44, v24, v44, s84
	v_add3_u32 v43, v25, v43, s84
	v_add3_u32 v24, v26, v42, s84
	v_add3_u32 v25, v27, v35, s84
	v_bfe_u32 v35, v32, 16, 1
	v_bfe_u32 v42, v33, 16, 1
	v_bfe_u32 v26, v22, 16, 1
	v_bfe_u32 v27, v23, 16, 1
	v_add3_u32 v33, v33, v42, s84
	v_add3_u32 v32, v32, v35, s84
	v_add3_u32 v23, v23, v27, s84
	v_add3_u32 v22, v22, v26, s84
	v_lshrrev_b32_e32 v26, 16, v32
	v_lshrrev_b32_e32 v27, 16, v33
	v_and_or_b32 v25, v25, s3, v27
	v_and_or_b32 v24, v24, s3, v26
	v_lshrrev_b32_e32 v22, 16, v22
	v_lshrrev_b32_e32 v23, 16, v23
	v_and_or_b32 v23, v43, s3, v23
	v_and_or_b32 v22, v44, s3, v22
	s_waitcnt vmcnt(1)
	v_lshlrev_b32_e32 v27, 16, v29
	v_lshlrev_b32_e32 v26, 16, v28
	v_and_b32_e32 v29, 0xffff0000, v29
	v_and_b32_e32 v28, 0xffff0000, v28
	v_lshlrev_b32_e32 v33, 16, v31
	v_lshlrev_b32_e32 v32, 16, v30
	v_and_b32_e32 v31, 0xffff0000, v31
	v_and_b32_e32 v30, 0xffff0000, v30
	v_pk_mul_f32 v[28:29], v[28:29], s[0:1] op_sel_hi:[1,0]
	v_pk_mul_f32 v[30:31], v[30:31], s[0:1] op_sel_hi:[1,0]
	v_pk_mul_f32 v[32:33], v[32:33], s[0:1] op_sel_hi:[1,0]
	v_bfe_u32 v35, v31, 16, 1
	v_bfe_u32 v42, v30, 16, 1
	v_bfe_u32 v43, v29, 16, 1
	v_bfe_u32 v44, v28, 16, 1
	v_pk_mul_f32 v[26:27], v[26:27], s[0:1] op_sel_hi:[1,0]
	v_add3_u32 v44, v28, v44, s84
	v_add3_u32 v43, v29, v43, s84
	v_add3_u32 v28, v30, v42, s84
	v_add3_u32 v29, v31, v35, s84
	v_bfe_u32 v35, v32, 16, 1
	v_bfe_u32 v42, v33, 16, 1
	v_bfe_u32 v30, v26, 16, 1
	v_bfe_u32 v31, v27, 16, 1
	v_add3_u32 v33, v33, v42, s84
	v_add3_u32 v32, v32, v35, s84
	v_add3_u32 v27, v27, v31, s84
	v_add3_u32 v26, v26, v30, s84
	v_lshrrev_b32_e32 v30, 16, v32
	v_lshrrev_b32_e32 v31, 16, v33
	v_and_or_b32 v29, v29, s3, v31
	v_and_or_b32 v28, v28, s3, v30
	s_waitcnt vmcnt(0)
; __device__ __forceinline__ void phase_xattn(CArgs& A, int l, unsigned char* lds, int tid) {
;     ...
;         const int skey = tid >> 3, sdc = (tid & 7) * 32;
;         const bf16* kvbase = KV + ((size_t)b * NMEM + skey) * 4096 + l * 2048 + h * 256 + sdc;
;         u32x4 kr[4], vr[4];
; #pragma unroll
;         for (int i = 0; i < 4; ++i) { kr[i] = *(const u32x4*)(kvbase + i * 8); vr[i] = *(const u32x4*)(kvbase + 1024 + i * 8); }
;         for (int kt = 0; kt < 4; ++kt) {
;             __syncthreads();
; #pragma unroll
;             for (int i = 0; i < 4; ++i) *(u32x4*)(Ks + skey * XA_KP + (sdc + i * 8) * 2) = kr[i];
; #pragma unroll
;             for (int i = 0; i < 4; ++i) *(u32x4*)(Vt + skey * XA_VP + (sdc + i * 8) * 2) = vr[i];
;             __syncthreads();
;             if (kt + 1 < 4) {
; #pragma unroll
;                 for (int i = 0; i < 4; ++i) { kr[i] = *(const u32x4*)(kvbase + (size_t)(kt + 1) * 64 * 4096 + i * 8); vr[i] = *(const u32x4*)(kvbase + (size_t)(kt + 1) * 64 * 4096 + 1024 + i * 8); } }
;             f32x4 sc[4];
; #pragma unroll
;             for (int blk = 0; blk < 4; ++blk) { sc[blk] = (f32x4){0.f, 0.f, 0.f, 0.f};
; #pragma unroll
;                 for (int ks = 0; ks < 8; ++ks) { const bf16x8 a = *(const bf16x8*)(Ks + (blk * 16 + r) * XA_KP + (32 * ks + 8 * g) * 2);
;                     sc[blk] = __builtin_amdgcn_mfma_f32_16x16x32_bf16(a, qf[ks], sc[blk], 0, 0, 0); } }
	v_lshlrev_b32_e32 v31, 16, v39
	v_lshlrev_b32_e32 v30, 16, v38
	v_and_b32_e32 v33, 0xffff0000, v39
	v_and_b32_e32 v32, 0xffff0000, v38
	v_lshlrev_b32_e32 v39, 16, v41
	v_lshlrev_b32_e32 v38, 16, v40
	v_and_b32_e32 v41, 0xffff0000, v41
	v_and_b32_e32 v40, 0xffff0000, v40
	v_lshrrev_b32_e32 v26, 16, v26
	v_lshrrev_b32_e32 v27, 16, v27
	v_pk_mul_f32 v[32:33], v[32:33], s[0:1] op_sel_hi:[1,0]
	v_pk_mul_f32 v[40:41], v[40:41], s[0:1] op_sel_hi:[1,0]
	v_and_or_b32 v27, v43, s3, v27
	v_and_or_b32 v26, v44, s3, v26
	v_pk_mul_f32 v[38:39], v[38:39], s[0:1] op_sel_hi:[1,0]
	v_bfe_u32 v35, v41, 16, 1
	v_bfe_u32 v42, v40, 16, 1
	v_bfe_u32 v43, v33, 16, 1
	v_bfe_u32 v44, v32, 16, 1
	v_pk_mul_f32 v[30:31], v[30:31], s[0:1] op_sel_hi:[1,0]
	v_add3_u32 v44, v32, v44, s84
	v_add3_u32 v43, v33, v43, s84
	v_add3_u32 v32, v40, v42, s84
	v_add3_u32 v33, v41, v35, s84
	v_bfe_u32 v41, v38, 16, 1
	v_bfe_u32 v42, v39, 16, 1
	v_bfe_u32 v35, v30, 16, 1
	v_add3_u32 v39, v39, v42, s84
	v_add3_u32 v38, v38, v41, s84
	v_add3_u32 v30, v30, v35, s84
	v_lshrrev_b32_e32 v35, 16, v38
	v_lshrrev_b32_e32 v38, 16, v39
	v_bfe_u32 v40, v31, 16, 1
	v_and_or_b32 v33, v33, s3, v38
	v_ashrrev_i32_e32 v38, 3, v1
	s_lshl_b64 s[0:1], s[4:5], 21
	v_add3_u32 v31, v31, v40, s84
	v_ashrrev_i32_e32 v39, 31, v38
	s_add_u32 s4, s9, s0
	v_lshrrev_b32_e32 v31, 16, v31
	s_addc_u32 s5, s10, s1
	v_lshlrev_b64 v[40:41], 13, v[38:39]
	v_and_or_b32 v31, v43, s3, v31
	v_lshl_add_u64 v[42:43], s[4:5], 0, v[40:41]
	v_and_or_b32 v32, v32, s3, v35
	v_lshl_add_u64 v[42:43], s[40:41], 1, v[42:43]
	v_lshlrev_b32_e32 v35, 6, v1
	v_lshl_add_u64 v[42:43], v[42:43], 0, s[14:15]
	v_and_b32_e32 v146, 0x1c0, v35
	v_lshl_add_u64 v[42:43], v[42:43], 0, v[146:147]
	global_load_dwordx4 v[98:101], v[42:43], off offset:48
	global_load_dwordx4 v[102:105], v[42:43], off offset:32
	global_load_dwordx4 v[106:109], v[42:43], off offset:16
	global_load_dwordx4 v[110:113], v[42:43], off
	global_load_dwordx4 v[114:117], v[42:43], off offset:2096
	global_load_dwordx4 v[118:121], v[42:43], off offset:2080
	global_load_dwordx4 v[122:125], v[42:43], off offset:2064
	global_load_dwordx4 v[126:129], v[42:43], off offset:2048
	v_add_u32_e32 v39, 0, v34
	v_cndmask_b32_e32 v34, v167, v178, vcc
	v_cmp_lt_i32_e32 vcc, v179, v173
	s_movk_i32 s4, 0x220
	v_lshlrev_b32_e32 v151, 2, v34
	v_cndmask_b32_e32 v34, v167, v179, vcc
	v_mul_lo_u32 v35, v38, s4
	v_lshlrev_b32_e32 v147, 2, v34
	v_bfe_u32 v34, v1, 2, 2
	v_add_u32_e32 v154, 0, v35
	v_or_b32_e32 v34, v143, v34
	v_lshlrev_b32_e32 v35, 3, v1
	v_and_b32_e32 v35, 24, v35
	v_mul_u32_u24_e32 v34, 0x220, v34
	v_add3_u32 v152, 0, v35, v34
	v_lshl_add_u64 v[34:35], s[0:1], 0, v[40:41]
	s_lshl_b32 s0, s11, 5
	s_and_b32 s0, s0, 0x600
	v_lshrrev_b32_e32 v30, 16, v30
	v_mov_b32_e32 v38, v154
	v_or3_b32 v34, v34, s0, v37
	v_and_or_b32 v30, v44, s3, v30
	v_lshl_add_u64 v[148:149], s[42:43], 0, v[34:35]
	v_add_u32_e32 v155, v38, v146
	v_add_u32_e32 v153, v39, v36
	v_mov_b32_e32 v34, 0
	v_mov_b32_e32 v35, v130
	v_mov_b32_e32 v36, v130
	v_mov_b32_e32 v37, v130
	v_mov_b32_e32 v38, 0
	v_mov_b32_e32 v39, v130
	v_mov_b32_e32 v40, v130
	v_mov_b32_e32 v41, v130
	v_mov_b32_e32 v42, 0
	v_mov_b32_e32 v43, v130
	v_mov_b32_e32 v44, v130
	v_mov_b32_e32 v45, v130
	v_mov_b32_e32 v46, 0
	v_mov_b32_e32 v47, v130
	v_mov_b32_e32 v48, v130
	v_mov_b32_e32 v49, v130
	v_mov_b32_e32 v50, 0
.LBB0_145:
	v_add_u32_e32 v157, v154, v146
	s_barrier
	s_waitcnt vmcnt(4)
	ds_write_b128 v157, v[110:113]
	ds_write_b128 v157, v[106:109] offset:16
	ds_write_b128 v157, v[102:105] offset:32
	ds_write_b128 v157, v[98:101] offset:48
	s_waitcnt vmcnt(0)
	ds_write_b128 v155, v[126:129] offset:34816
	ds_write_b128 v155, v[122:125] offset:34832
	ds_write_b128 v155, v[118:121] offset:34848
	ds_write_b128 v155, v[114:117] offset:34864
	v_lshl_add_u64 v[126:127], v[148:149], 0, s[44:45]
	v_mov_b32_e32 v158, v130
	s_waitcnt lgkmcnt(0)
	s_barrier
	ds_read_b128 v[204:207], v153
	ds_read_b128 v[208:211], v153 offset:64
	ds_read_b128 v[212:215], v153 offset:128
	ds_read_b128 v[216:219], v153 offset:192
	ds_read_b128 v[220:223], v153 offset:256
	ds_read_b128 v[224:227], v153 offset:320
	ds_read_b128 v[228:231], v153 offset:384
	ds_read_b128 v[232:235], v153 offset:448
	ds_read_b128 v[236:239], v153 offset:8704
	ds_read_b128 v[240:243], v153 offset:8768
	ds_read_b128 v[244:247], v153 offset:8832
	global_load_dwordx4 v[98:101], v[126:127], off offset:-2000
	global_load_dwordx4 v[102:105], v[126:127], off offset:-2016
	global_load_dwordx4 v[106:109], v[126:127], off offset:-2032
	global_load_dwordx4 v[110:113], v[126:127], off offset:-2048
	global_load_dwordx4 v[114:117], v[126:127], off offset:48
	global_load_dwordx4 v[118:121], v[126:127], off offset:32
	global_load_dwordx4 v[122:125], v[126:127], off offset:16
	s_nop 0
	global_load_dwordx4 v[126:129], v[126:127], off
	s_waitcnt lgkmcnt(10)
	s_nop 0
	s_nop 0
	v_mfma_f32_16x16x32_bf16 v[130:133], v[204:207], v[6:9], 0
	ds_read_b128 v[204:207], v153 offset:8896
	v_mov_b32_e32 v150, v156
	s_add_u32 s44, s44, 0x80000
	s_waitcnt lgkmcnt(10)
	v_mfma_f32_16x16x32_bf16 v[130:133], v[208:211], v[2:5], v[130:133]
	ds_read_b128 v[208:211], v153 offset:8960
	s_nop 0
	s_addc_u32 s45, s45, 0
	s_waitcnt lgkmcnt(10)
	v_mfma_f32_16x16x32_bf16 v[130:133], v[212:215], v[10:13], v[130:133]
	ds_read_b128 v[212:215], v153 offset:9024
	s_nop 0
	s_cmp_eq_u32 s44, 0x180000
	s_waitcnt lgkmcnt(10)
	v_mfma_f32_16x16x32_bf16 v[130:133], v[216:219], v[14:17], v[130:133]
	ds_read_b128 v[216:219], v153 offset:9088
	s_waitcnt lgkmcnt(10)
	v_mfma_f32_16x16x32_bf16 v[130:133], v[220:223], v[18:21], v[130:133]
	ds_read_b128 v[220:223], v153 offset:9152
	s_waitcnt lgkmcnt(10)
; #define LAS __attribute__((address_space(3)))
; __device__ __forceinline__ void phase_xattn(CArgs& A, int l, unsigned char* lds, int tid) {
;     ...
;             f32x4 sc[4];
; #pragma unroll
;             for (int blk = 0; blk < 4; ++blk) { sc[blk] = (f32x4){0.f, 0.f, 0.f, 0.f};
; #pragma unroll
;                 for (int ks = 0; ks < 8; ++ks) { const bf16x8 a = *(const bf16x8*)(Ks + (blk * 16 + r) * XA_KP + (32 * ks + 8 * g) * 2);
;                     sc[blk] = __builtin_amdgcn_mfma_f32_16x16x32_bf16(a, qf[ks], sc[blk], 0, 0, 0); } }
;             float mx = -INFINITY;
; #pragma unroll
;             for (int blk = 0; blk < 4; ++blk)
; #pragma unroll
;                 for (int e = 0; e < 4; ++e) { sc[blk][e] *= LOG2E; mx = fmaxf(mx, sc[blk][e]); }
;             mx = fmaxf(mx, __shfl_xor(mx, 16)); mx = fmaxf(mx, __shfl_xor(mx, 32));
;     ...
;                 for (int db = 0; db < 16; ++db) { const unsigned char* vp = Vt + (32 * m2 + 4 * g + (r >> 2)) * XA_VP + (16 * db + 4 * (r & 3)) * 2;
;                     const s16x4 lo = __builtin_amdgcn_ds_read_tr16_b64_v4i16((LAS s16x4*)vp), hi = __builtin_amdgcn_ds_read_tr16_b64_v4i16((LAS s16x4*)(vp + 16 * XA_VP));
	v_mfma_f32_16x16x32_bf16 v[130:133], v[224:227], v[22:25], v[130:133]
	ds_read_b128 v[224:227], v153 offset:17408
	s_waitcnt lgkmcnt(10)
	v_mfma_f32_16x16x32_bf16 v[130:133], v[228:231], v[26:29], v[130:133]
	ds_read_b128 v[228:231], v153 offset:17472
	s_waitcnt lgkmcnt(10)
	v_mfma_f32_16x16x32_bf16 v[130:133], v[232:235], v[30:33], v[130:133]
	ds_read_b128 v[232:235], v153 offset:17536
	s_nop 6
	v_mul_f32_e32 v156, 0x3fb8aa3b, v130
	s_waitcnt lgkmcnt(10)
	v_mfma_f32_16x16x32_bf16 v[134:137], v[236:239], v[6:9], 0
	ds_read_b128 v[236:239], v153 offset:17600
	v_mul_f32_e32 v159, 0x3fb8aa3b, v131
	v_max3_f32 v156, v156, s78, v159
	v_mul_f32_e32 v159, 0x3fb8aa3b, v132
	s_waitcnt lgkmcnt(10)
	v_mfma_f32_16x16x32_bf16 v[134:137], v[240:243], v[2:5], v[134:137]
	ds_read_b128 v[240:243], v153 offset:17664
	v_mul_f32_e32 v160, 0x3fb8aa3b, v133
	v_max3_f32 v156, v156, v159, v160
	s_waitcnt lgkmcnt(10)
	v_mfma_f32_16x16x32_bf16 v[134:137], v[244:247], v[10:13], v[134:137]
	ds_read_b128 v[244:247], v153 offset:17728
	s_waitcnt lgkmcnt(10)
	v_mfma_f32_16x16x32_bf16 v[134:137], v[204:207], v[14:17], v[134:137]
	ds_read_b128 v[204:207], v153 offset:17792
	s_waitcnt lgkmcnt(10)
	v_mfma_f32_16x16x32_bf16 v[134:137], v[208:211], v[18:21], v[134:137]
	ds_read_b128 v[208:211], v153 offset:17856
	s_waitcnt lgkmcnt(10)
	v_mfma_f32_16x16x32_bf16 v[134:137], v[212:215], v[22:25], v[134:137]
	ds_read_b128 v[212:215], v153 offset:26112
	s_waitcnt lgkmcnt(10)
	v_mfma_f32_16x16x32_bf16 v[134:137], v[216:219], v[26:29], v[134:137]
	ds_read_b128 v[216:219], v153 offset:26176
	s_waitcnt lgkmcnt(10)
	v_mfma_f32_16x16x32_bf16 v[134:137], v[220:223], v[30:33], v[134:137]
	ds_read_b128 v[220:223], v153 offset:26240
	s_nop 6
	v_mul_f32_e32 v159, 0x3fb8aa3b, v134
	s_waitcnt lgkmcnt(10)
	v_mfma_f32_16x16x32_bf16 v[138:141], v[224:227], v[6:9], 0
	ds_read_b128 v[224:227], v153 offset:26304
	v_mul_f32_e32 v160, 0x3fb8aa3b, v135
	v_max3_f32 v156, v156, v159, v160
	v_mul_f32_e32 v159, 0x3fb8aa3b, v136
	s_waitcnt lgkmcnt(10)
	v_mfma_f32_16x16x32_bf16 v[138:141], v[228:231], v[2:5], v[138:141]
	ds_read_b128 v[228:231], v153 offset:26368
	v_mul_f32_e32 v160, 0x3fb8aa3b, v137
	v_max3_f32 v156, v156, v159, v160
	s_waitcnt lgkmcnt(10)
	v_mfma_f32_16x16x32_bf16 v[138:141], v[232:235], v[10:13], v[138:141]
	ds_read_b128 v[232:235], v153 offset:26432
	s_waitcnt lgkmcnt(10)
	v_mfma_f32_16x16x32_bf16 v[138:141], v[236:239], v[14:17], v[138:141]
	ds_read_b128 v[236:239], v153 offset:26496
	s_waitcnt lgkmcnt(10)
	v_mfma_f32_16x16x32_bf16 v[138:141], v[240:243], v[18:21], v[138:141]
	ds_read_b128 v[240:243], v153 offset:26560
	s_waitcnt lgkmcnt(10)
	v_mfma_f32_16x16x32_bf16 v[138:141], v[244:247], v[22:25], v[138:141]
	ds_read_b64_tr_b16 v[244:245], v152 offset:34816
	ds_read_b64_tr_b16 v[246:247], v152 offset:43520
	s_waitcnt lgkmcnt(11)
	v_mfma_f32_16x16x32_bf16 v[138:141], v[204:207], v[26:29], v[138:141]
	ds_read_b64_tr_b16 v[204:205], v152 offset:34880
	ds_read_b64_tr_b16 v[206:207], v152 offset:43584
	s_waitcnt lgkmcnt(12)
	v_mfma_f32_16x16x32_bf16 v[138:141], v[208:211], v[30:33], v[138:141]
	s_nop 0
	s_nop 6
	v_mul_f32_e32 v159, 0x3fb8aa3b, v138
	s_waitcnt lgkmcnt(11)
	v_mfma_f32_16x16x32_bf16 v[192:195], v[212:215], v[6:9], 0
	ds_read_b64_tr_b16 v[208:209], v152 offset:34912
	ds_read_b64_tr_b16 v[210:211], v152 offset:43616
	v_mul_f32_e32 v160, 0x3fb8aa3b, v139
	v_max3_f32 v156, v156, v159, v160
	v_mul_f32_e32 v159, 0x3fb8aa3b, v140
	s_waitcnt lgkmcnt(12)
	v_mfma_f32_16x16x32_bf16 v[192:195], v[216:219], v[2:5], v[192:195]
	s_nop 0
	v_mul_f32_e32 v160, 0x3fb8aa3b, v141
	v_max3_f32 v156, v156, v159, v160
	s_waitcnt lgkmcnt(11)
	v_mfma_f32_16x16x32_bf16 v[192:195], v[220:223], v[10:13], v[192:195]
	ds_read_b64_tr_b16 v[212:213], v152 offset:34944
	ds_read_b64_tr_b16 v[214:215], v152 offset:43648
	s_waitcnt lgkmcnt(12)
	v_mfma_f32_16x16x32_bf16 v[192:195], v[224:227], v[14:17], v[192:195]
	s_waitcnt lgkmcnt(11)
	s_nop 0
	v_mfma_f32_16x16x32_bf16 v[192:195], v[228:231], v[18:21], v[192:195]
	ds_read_b64_tr_b16 v[216:217], v152 offset:34976
	ds_read_b64_tr_b16 v[218:219], v152 offset:43680
	s_waitcnt lgkmcnt(12)
	v_mfma_f32_16x16x32_bf16 v[192:195], v[232:235], v[22:25], v[192:195]
	s_waitcnt lgkmcnt(11)
	s_nop 0
	v_mfma_f32_16x16x32_bf16 v[192:195], v[236:239], v[26:29], v[192:195]
	ds_read_b64_tr_b16 v[220:221], v152 offset:35008
	ds_read_b64_tr_b16 v[222:223], v152 offset:43712
	s_waitcnt lgkmcnt(12)
	v_mfma_f32_16x16x32_bf16 v[192:195], v[240:243], v[30:33], v[192:195]
	s_nop 7
	v_mul_f32_e32 v159, 0x3fb8aa3b, v192
	v_mul_f32_e32 v160, 0x3fb8aa3b, v193
	v_max3_f32 v156, v156, v159, v160
	v_mul_f32_e32 v159, 0x3fb8aa3b, v194
	v_mul_f32_e32 v160, 0x3fb8aa3b, v195
	v_max3_f32 v156, v156, v159, v160
	ds_bpermute_b32 v159, v151, v156
	s_waitcnt lgkmcnt(0)
	v_max_f32_e32 v159, v159, v159
	v_max_f32_e32 v156, v156, v159
	ds_bpermute_b32 v159, v147, v156
	s_waitcnt lgkmcnt(0)
; #define LAS __attribute__((address_space(3)))
; __device__ __forceinline__ void phase_xattn(CArgs& A, int l, unsigned char* lds, int tid) {
;     ...
;             const float mnew = fmaxf(m, mx); const float corr = __builtin_amdgcn_exp2f(m - mnew); m = mnew;
;             float ps = 0.f;
; #pragma unroll
;             for (int blk = 0; blk < 4; ++blk)
; #pragma unroll
;                 for (int e = 0; e < 4; ++e) { sc[blk][e] = __builtin_amdgcn_exp2f(sc[blk][e] - mnew); ps += sc[blk][e]; }
;             lsum = lsum * corr + ps;
; #pragma unroll
;             for (int i = 0; i < 16; ++i) o[i] *= corr;
; #pragma unroll
;             for (int m2 = 0; m2 < 2; ++m2) {
;                 const bf16x8 pb = pack_frag(sc[2 * m2][0], sc[2 * m2][1], sc[2 * m2][2], sc[2 * m2][3], sc[2 * m2 + 1][0], sc[2 * m2 + 1][1], sc[2 * m2 + 1][2], sc[2 * m2 + 1][3]);
; #pragma unroll
;                 for (int db = 0; db < 16; ++db) { const unsigned char* vp = Vt + (32 * m2 + 4 * g + (r >> 2)) * XA_VP + (16 * db + 4 * (r & 3)) * 2;
;                     const s16x4 lo = __builtin_amdgcn_ds_read_tr16_b64_v4i16((LAS s16x4*)vp), hi = __builtin_amdgcn_ds_read_tr16_b64_v4i16((LAS s16x4*)(vp + 16 * XA_VP));
;                     bf16x8 av; av[0] = lo[0]; av[1] = lo[1]; av[2] = lo[2]; av[3] = lo[3]; av[4] = hi[0]; av[5] = hi[1]; av[6] = hi[2]; av[7] = hi[3];
;                     o[db] = __builtin_amdgcn_mfma_f32_16x16x32_bf16(av, pb, o[db], 0, 0, 0); }
	v_max3_f32 v156, v150, v156, v159
	v_fma_f32 v132, v132, s83, -v156
	v_exp_f32_e32 v160, v132
	v_fma_f32 v132, v133, s83, -v156
	v_fma_f32 v130, v130, s83, -v156
	v_exp_f32_e32 v133, v132
	v_fma_f32 v132, v134, s83, -v156
	v_exp_f32_e32 v159, v130
	v_fma_f32 v131, v131, s83, -v156
	v_exp_f32_e32 v134, v132
	v_fma_f32 v132, v135, s83, -v156
	v_exp_f32_e32 v131, v131
	v_exp_f32_e32 v135, v132
	v_fma_f32 v132, v136, s83, -v156
	v_exp_f32_e32 v136, v132
	v_fma_f32 v132, v137, s83, -v156
	v_exp_f32_e32 v137, v132
	v_fma_f32 v132, v138, s83, -v156
	v_add_f32_e32 v130, 0, v159
	v_exp_f32_e32 v161, v132
	v_fma_f32 v132, v139, s83, -v156
	v_add_f32_e32 v130, v131, v130
	v_exp_f32_e32 v196, v132
	v_fma_f32 v132, v140, s83, -v156
	v_add_f32_e32 v130, v160, v130
	v_exp_f32_e32 v140, v132
	v_fma_f32 v132, v141, s83, -v156
	v_add_f32_e32 v130, v133, v130
	v_exp_f32_e32 v141, v132
	v_fma_f32 v132, v192, s83, -v156
	v_add_f32_e32 v130, v134, v130
	v_exp_f32_e32 v197, v132
	v_fma_f32 v132, v193, s83, -v156
	v_sub_f32_e32 v150, v150, v156
	v_add_f32_e32 v130, v135, v130
	v_exp_f32_e32 v198, v132
	v_fma_f32 v132, v194, s83, -v156
	v_exp_f32_e32 v150, v150
	v_add_f32_e32 v130, v136, v130
	v_exp_f32_e32 v199, v132
	v_fma_f32 v132, v195, s83, -v156
	v_add_f32_e32 v130, v137, v130
	v_exp_f32_e32 v200, v132
	v_cvt_pk_bf16_f32 v132, v159, v131
	v_cvt_pk_bf16_f32 v133, v160, v133
	v_cvt_pk_bf16_f32 v134, v134, v135
	v_cvt_pk_bf16_f32 v135, v136, v137
	s_nop 0
	s_nop 0
	s_nop 0
	v_pk_mul_f32 v[88:89], v[88:89], v[150:151] op_sel_hi:[1,0]
	v_pk_mul_f32 v[86:87], v[86:87], v[150:151] op_sel_hi:[1,0]
	s_nop 0
	v_pk_mul_f32 v[64:65], v[64:65], v[150:151] op_sel_hi:[1,0]
	s_nop 0
	v_mfma_f32_16x16x32_bf16 v[86:89], v[244:247], v[132:135], v[86:89]
	ds_read_b64_tr_b16 v[224:225], v152 offset:35040
	ds_read_b64_tr_b16 v[226:227], v152 offset:43744
	ds_read_b64_tr_b16 v[228:229], v152 offset:35072
	ds_read_b64_tr_b16 v[230:231], v152 offset:43776
	ds_read_b64_tr_b16 v[232:233], v152 offset:35104
	ds_read_b64_tr_b16 v[234:235], v152 offset:43808
	ds_read_b64_tr_b16 v[236:237], v152 offset:35136
	ds_read_b64_tr_b16 v[238:239], v152 offset:43840
	ds_read_b64_tr_b16 v[240:241], v152 offset:35168
	ds_read_b64_tr_b16 v[242:243], v152 offset:43872
	ds_read_b64_tr_b16 v[244:245], v152 offset:35200
	ds_read_b64_tr_b16 v[246:247], v152 offset:43904
	v_pk_mul_f32 v[62:63], v[62:63], v[150:151] op_sel_hi:[1,0]
	v_pk_mul_f32 v[72:73], v[72:73], v[150:151] op_sel_hi:[1,0]
	v_pk_mul_f32 v[70:71], v[70:71], v[150:151] op_sel_hi:[1,0]
	s_nop 0
	v_mfma_f32_16x16x32_bf16 v[62:65], v[204:207], v[132:135], v[62:65]
	s_nop 0
	s_nop 0
	v_pk_mul_f32 v[80:81], v[80:81], v[150:151] op_sel_hi:[1,0]
	v_pk_mul_f32 v[78:79], v[78:79], v[150:151] op_sel_hi:[1,0]
	s_nop 0
	v_mfma_f32_16x16x32_bf16 v[70:73], v[208:211], v[132:135], v[70:73]
	s_nop 0
	s_nop 0
	v_pk_mul_f32 v[92:93], v[92:93], v[150:151] op_sel_hi:[1,0]
	v_pk_mul_f32 v[90:91], v[90:91], v[150:151] op_sel_hi:[1,0]
	s_nop 0
	v_mfma_f32_16x16x32_bf16 v[78:81], v[212:215], v[132:135], v[78:81]
	s_nop 0
	s_nop 0
	v_pk_mul_f32 v[84:85], v[84:85], v[150:151] op_sel_hi:[1,0]
	v_pk_mul_f32 v[82:83], v[82:83], v[150:151] op_sel_hi:[1,0]
	s_nop 0
	v_mfma_f32_16x16x32_bf16 v[90:93], v[216:219], v[132:135], v[90:93]
	s_nop 0
	s_nop 0
	v_pk_mul_f32 v[96:97], v[96:97], v[150:151] op_sel_hi:[1,0]
	v_pk_mul_f32 v[94:95], v[94:95], v[150:151] op_sel_hi:[1,0]
	s_nop 0
	v_mfma_f32_16x16x32_bf16 v[82:85], v[220:223], v[132:135], v[82:85]
	s_nop 0
	s_nop 0
	v_pk_mul_f32 v[76:77], v[76:77], v[150:151] op_sel_hi:[1,0]
	v_pk_mul_f32 v[74:75], v[74:75], v[150:151] op_sel_hi:[1,0]
	s_waitcnt lgkmcnt(10)
	v_mfma_f32_16x16x32_bf16 v[94:97], v[224:227], v[132:135], v[94:97]
	ds_read_b64_tr_b16 v[204:205], v152 offset:35232
	ds_read_b64_tr_b16 v[206:207], v152 offset:43936
	v_pk_mul_f32 v[60:61], v[60:61], v[150:151] op_sel_hi:[1,0]
	v_pk_mul_f32 v[58:59], v[58:59], v[150:151] op_sel_hi:[1,0]
	s_waitcnt lgkmcnt(10)
	v_mfma_f32_16x16x32_bf16 v[74:77], v[228:231], v[132:135], v[74:77]
	ds_read_b64_tr_b16 v[208:209], v152 offset:35264
	ds_read_b64_tr_b16 v[210:211], v152 offset:43968
	v_pk_mul_f32 v[56:57], v[56:57], v[150:151] op_sel_hi:[1,0]
	v_pk_mul_f32 v[54:55], v[54:55], v[150:151] op_sel_hi:[1,0]
	s_waitcnt lgkmcnt(10)
	v_mfma_f32_16x16x32_bf16 v[58:61], v[232:235], v[132:135], v[58:61]
	ds_read_b64_tr_b16 v[212:213], v152 offset:34848
	ds_read_b64_tr_b16 v[214:215], v152 offset:43552
	v_pk_mul_f32 v[52:53], v[52:53], v[150:151] op_sel_hi:[1,0]
	v_pk_mul_f32 v[50:51], v[50:51], v[150:151] op_sel_hi:[1,0]
	s_waitcnt lgkmcnt(10)
	v_mfma_f32_16x16x32_bf16 v[54:57], v[236:239], v[132:135], v[54:57]
	ds_read_b64_tr_b16 v[216:217], v152 offset:35296
	ds_read_b64_tr_b16 v[218:219], v152 offset:44000
	v_pk_mul_f32 v[48:49], v[48:49], v[150:151] op_sel_hi:[1,0]
	v_pk_mul_f32 v[46:47], v[46:47], v[150:151] op_sel_hi:[1,0]
	s_waitcnt lgkmcnt(10)
	v_mfma_f32_16x16x32_bf16 v[50:53], v[240:243], v[132:135], v[50:53]
	ds_read_b64_tr_b16 v[220:221], v152 offset:52224
	ds_read_b64_tr_b16 v[222:223], v152 offset:60928
	v_pk_mul_f32 v[44:45], v[44:45], v[150:151] op_sel_hi:[1,0]
	v_pk_mul_f32 v[42:43], v[42:43], v[150:151] op_sel_hi:[1,0]
	s_waitcnt lgkmcnt(10)
	v_mfma_f32_16x16x32_bf16 v[46:49], v[244:247], v[132:135], v[46:49]
	ds_read_b64_tr_b16 v[224:225], v152 offset:52288
	ds_read_b64_tr_b16 v[226:227], v152 offset:60992
	v_pk_mul_f32 v[40:41], v[40:41], v[150:151] op_sel_hi:[1,0]
	v_pk_mul_f32 v[38:39], v[38:39], v[150:151] op_sel_hi:[1,0]
	s_waitcnt lgkmcnt(10)
; #define LAS __attribute__((address_space(3)))
; __device__ __forceinline__ void phase_xattn(CArgs& A, int l, unsigned char* lds, int tid) {
;     ...
;         for (int kt = 0; kt < 4; ++kt) {
;             __syncthreads();
; #pragma unroll
;             for (int i = 0; i < 4; ++i) *(u32x4*)(Ks + skey * XA_KP + (sdc + i * 8) * 2) = kr[i];
; #pragma unroll
;             for (int i = 0; i < 4; ++i) *(u32x4*)(Vt + skey * XA_VP + (sdc + i * 8) * 2) = vr[i];
;             __syncthreads();
;     ...
;             for (int m2 = 0; m2 < 2; ++m2) {
;                 const bf16x8 pb = pack_frag(sc[2 * m2][0], sc[2 * m2][1], sc[2 * m2][2], sc[2 * m2][3], sc[2 * m2 + 1][0], sc[2 * m2 + 1][1], sc[2 * m2 + 1][2], sc[2 * m2 + 1][3]);
; #pragma unroll
;                 for (int db = 0; db < 16; ++db) { const unsigned char* vp = Vt + (32 * m2 + 4 * g + (r >> 2)) * XA_VP + (16 * db + 4 * (r & 3)) * 2;
;                     const s16x4 lo = __builtin_amdgcn_ds_read_tr16_b64_v4i16((LAS s16x4*)vp), hi = __builtin_amdgcn_ds_read_tr16_b64_v4i16((LAS s16x4*)(vp + 16 * XA_VP));
;                     bf16x8 av; av[0] = lo[0]; av[1] = lo[1]; av[2] = lo[2]; av[3] = lo[3]; av[4] = hi[0]; av[5] = hi[1]; av[6] = hi[2]; av[7] = hi[3];
;                     o[db] = __builtin_amdgcn_mfma_f32_16x16x32_bf16(av, pb, o[db], 0, 0, 0); }
	v_mfma_f32_16x16x32_bf16 v[42:45], v[204:207], v[132:135], v[42:45]
	ds_read_b64_tr_b16 v[228:229], v152 offset:52320
	ds_read_b64_tr_b16 v[230:231], v152 offset:61024
	v_pk_mul_f32 v[68:69], v[68:69], v[150:151] op_sel_hi:[1,0]
	v_pk_mul_f32 v[66:67], v[66:67], v[150:151] op_sel_hi:[1,0]
	s_waitcnt lgkmcnt(10)
	v_mfma_f32_16x16x32_bf16 v[38:41], v[208:211], v[132:135], v[38:41]
	ds_read_b64_tr_b16 v[232:233], v152 offset:52352
	ds_read_b64_tr_b16 v[234:235], v152 offset:61056
	v_pk_mul_f32 v[36:37], v[36:37], v[150:151] op_sel_hi:[1,0]
	v_pk_mul_f32 v[34:35], v[34:35], v[150:151] op_sel_hi:[1,0]
	s_waitcnt lgkmcnt(10)
	v_mfma_f32_16x16x32_bf16 v[66:69], v[212:215], v[132:135], v[66:69]
	ds_read_b64_tr_b16 v[236:237], v152 offset:52384
	ds_read_b64_tr_b16 v[238:239], v152 offset:61088
	v_add_f32_e32 v130, v161, v130
	v_add_f32_e32 v130, v196, v130
	v_add_f32_e32 v130, v140, v130
	s_waitcnt lgkmcnt(10)
	v_mfma_f32_16x16x32_bf16 v[34:37], v[216:219], v[132:135], v[34:37]
	ds_read_b64_tr_b16 v[240:241], v152 offset:52416
	ds_read_b64_tr_b16 v[242:243], v152 offset:61120
	v_cvt_pk_bf16_f32 v132, v161, v196
	v_cvt_pk_bf16_f32 v133, v140, v141
	v_cvt_pk_bf16_f32 v134, v197, v198
	v_cvt_pk_bf16_f32 v135, v199, v200
	s_waitcnt lgkmcnt(10)
	s_nop 0
	s_nop 0
	s_nop 0
	v_mfma_f32_16x16x32_bf16 v[86:89], v[220:223], v[132:135], v[86:89]
	ds_read_b64_tr_b16 v[244:245], v152 offset:52448
	ds_read_b64_tr_b16 v[246:247], v152 offset:61152
	s_nop 0
	v_add_f32_e32 v130, v141, v130
	s_waitcnt lgkmcnt(10)
	v_mfma_f32_16x16x32_bf16 v[62:65], v[224:227], v[132:135], v[62:65]
	ds_read_b64_tr_b16 v[204:205], v152 offset:52480
	ds_read_b64_tr_b16 v[206:207], v152 offset:61184
	v_add_f32_e32 v130, v197, v130
	v_add_f32_e32 v130, v198, v130
	s_waitcnt lgkmcnt(10)
	v_mfma_f32_16x16x32_bf16 v[70:73], v[228:231], v[132:135], v[70:73]
	ds_read_b64_tr_b16 v[208:209], v152 offset:52512
	ds_read_b64_tr_b16 v[210:211], v152 offset:61216
	v_add_f32_e32 v130, v199, v130
	v_add_f32_e32 v130, v200, v130
	s_waitcnt lgkmcnt(10)
	v_mfma_f32_16x16x32_bf16 v[78:81], v[232:235], v[132:135], v[78:81]
	ds_read_b64_tr_b16 v[212:213], v152 offset:52544
	ds_read_b64_tr_b16 v[214:215], v152 offset:61248
	v_fmac_f32_e32 v130, v158, v150
	s_waitcnt lgkmcnt(10)
	v_mfma_f32_16x16x32_bf16 v[90:93], v[236:239], v[132:135], v[90:93]
	ds_read_b64_tr_b16 v[216:217], v152 offset:52576
	ds_read_b64_tr_b16 v[218:219], v152 offset:61280
	s_waitcnt lgkmcnt(10)
	v_mfma_f32_16x16x32_bf16 v[82:85], v[240:243], v[132:135], v[82:85]
	ds_read_b64_tr_b16 v[220:221], v152 offset:52608
	ds_read_b64_tr_b16 v[222:223], v152 offset:61312
	s_waitcnt lgkmcnt(10)
	v_mfma_f32_16x16x32_bf16 v[94:97], v[244:247], v[132:135], v[94:97]
	ds_read_b64_tr_b16 v[224:225], v152 offset:52640
	ds_read_b64_tr_b16 v[226:227], v152 offset:61344
	s_waitcnt lgkmcnt(10)
	v_mfma_f32_16x16x32_bf16 v[74:77], v[204:207], v[132:135], v[74:77]
	ds_read_b64_tr_b16 v[228:229], v152 offset:52672
	ds_read_b64_tr_b16 v[230:231], v152 offset:61376
	s_waitcnt lgkmcnt(10)
	v_mfma_f32_16x16x32_bf16 v[58:61], v[208:211], v[132:135], v[58:61]
	ds_read_b64_tr_b16 v[232:233], v152 offset:52256
	ds_read_b64_tr_b16 v[234:235], v152 offset:60960
	s_waitcnt lgkmcnt(10)
	v_mfma_f32_16x16x32_bf16 v[54:57], v[212:215], v[132:135], v[54:57]
	ds_read_b64_tr_b16 v[236:237], v152 offset:52704
	ds_read_b64_tr_b16 v[238:239], v152 offset:61408
	s_waitcnt lgkmcnt(10)
	v_mfma_f32_16x16x32_bf16 v[50:53], v[216:219], v[132:135], v[50:53]
	s_waitcnt lgkmcnt(8)
	s_nop 0
	s_nop 0
	v_mfma_f32_16x16x32_bf16 v[46:49], v[220:223], v[132:135], v[46:49]
	s_waitcnt lgkmcnt(6)
	s_nop 0
	s_nop 0
	v_mfma_f32_16x16x32_bf16 v[42:45], v[224:227], v[132:135], v[42:45]
	s_waitcnt lgkmcnt(4)
	s_nop 0
	s_nop 0
	v_mfma_f32_16x16x32_bf16 v[38:41], v[228:231], v[132:135], v[38:41]
	s_waitcnt lgkmcnt(2)
	s_nop 0
	v_mfma_f32_16x16x32_bf16 v[66:69], v[232:235], v[132:135], v[66:69]
	s_waitcnt lgkmcnt(0)
	v_mfma_f32_16x16x32_bf16 v[34:37], v[236:239], v[132:135], v[34:37]
	s_cbranch_scc0 .LBB0_145
	s_barrier
	s_waitcnt vmcnt(4)
	ds_write_b128 v157, v[110:113]
	ds_write_b128 v157, v[106:109] offset:16
	ds_write_b128 v157, v[102:105] offset:32
	ds_write_b128 v157, v[98:101] offset:48
	s_waitcnt vmcnt(0)
	ds_write_b128 v155, v[126:129] offset:34816
	ds_write_b128 v155, v[122:125] offset:34832
	ds_write_b128 v155, v[118:121] offset:34848
	ds_write_b128 v155, v[114:117] offset:34864
	s_waitcnt lgkmcnt(0)
	s_barrier
; __device__ __forceinline__ void phase_xattn(CArgs& A, int l, unsigned char* lds, int tid) {
;     ...
;             f32x4 sc[4];
; #pragma unroll
;             for (int blk = 0; blk < 4; ++blk) { sc[blk] = (f32x4){0.f, 0.f, 0.f, 0.f};
; #pragma unroll
;                 for (int ks = 0; ks < 8; ++ks) { const bf16x8 a = *(const bf16x8*)(Ks + (blk * 16 + r) * XA_KP + (32 * ks + 8 * g) * 2);
;                     sc[blk] = __builtin_amdgcn_mfma_f32_16x16x32_bf16(a, qf[ks], sc[blk], 0, 0, 0); } }
;             float mx = -INFINITY;
; #pragma unroll
;             for (int blk = 0; blk < 4; ++blk)
; #pragma unroll
;                 for (int e = 0; e < 4; ++e) { sc[blk][e] *= LOG2E; mx = fmaxf(mx, sc[blk][e]); }
;             mx = fmaxf(mx, __shfl_xor(mx, 16)); mx = fmaxf(mx, __shfl_xor(mx, 32));
	ds_read_b128 v[204:207], v153
	ds_read_b128 v[208:211], v153 offset:64
	ds_read_b128 v[212:215], v153 offset:128
	ds_read_b128 v[216:219], v153 offset:192
	ds_read_b128 v[220:223], v153 offset:256
	ds_read_b128 v[224:227], v153 offset:320
	ds_read_b128 v[228:231], v153 offset:384
	ds_read_b128 v[232:235], v153 offset:448
	ds_read_b128 v[236:239], v153 offset:8704
	ds_read_b128 v[240:243], v153 offset:8768
	ds_read_b128 v[244:247], v153 offset:8832
	s_waitcnt lgkmcnt(10)
	v_mfma_f32_16x16x32_bf16 v[98:101], v[204:207], v[6:9], 0
	ds_read_b128 v[204:207], v153 offset:8896
	s_lshl_b32 s14, s36, 1
	s_waitcnt lgkmcnt(10)
	s_nop 0
	v_mfma_f32_16x16x32_bf16 v[98:101], v[208:211], v[2:5], v[98:101]
	ds_read_b128 v[208:211], v153 offset:8960
	s_waitcnt lgkmcnt(10)
	v_mfma_f32_16x16x32_bf16 v[98:101], v[212:215], v[10:13], v[98:101]
	ds_read_b128 v[212:215], v153 offset:9024
	s_waitcnt lgkmcnt(10)
	v_mfma_f32_16x16x32_bf16 v[98:101], v[216:219], v[14:17], v[98:101]
	ds_read_b128 v[216:219], v153 offset:9088
	s_waitcnt lgkmcnt(10)
	v_mfma_f32_16x16x32_bf16 v[98:101], v[220:223], v[18:21], v[98:101]
	ds_read_b128 v[220:223], v153 offset:9152
	s_waitcnt lgkmcnt(10)
	v_mfma_f32_16x16x32_bf16 v[98:101], v[224:227], v[22:25], v[98:101]
	ds_read_b128 v[224:227], v153 offset:17408
	s_waitcnt lgkmcnt(10)
	v_mfma_f32_16x16x32_bf16 v[98:101], v[228:231], v[26:29], v[98:101]
	ds_read_b128 v[228:231], v153 offset:17472
	s_waitcnt lgkmcnt(10)
	v_mfma_f32_16x16x32_bf16 v[98:101], v[232:235], v[30:33], v[98:101]
	ds_read_b128 v[232:235], v153 offset:17536
	s_waitcnt lgkmcnt(10)
	v_mfma_f32_16x16x32_bf16 v[102:105], v[236:239], v[6:9], 0
	ds_read_b128 v[236:239], v153 offset:17600
	s_waitcnt lgkmcnt(10)
	v_mfma_f32_16x16x32_bf16 v[102:105], v[240:243], v[2:5], v[102:105]
	ds_read_b128 v[240:243], v153 offset:17664
	s_waitcnt lgkmcnt(10)
	v_mfma_f32_16x16x32_bf16 v[102:105], v[244:247], v[10:13], v[102:105]
	ds_read_b128 v[244:247], v153 offset:17728
	s_waitcnt lgkmcnt(10)
	v_mfma_f32_16x16x32_bf16 v[102:105], v[204:207], v[14:17], v[102:105]
	ds_read_b128 v[204:207], v153 offset:17792
	s_waitcnt lgkmcnt(10)
	v_mfma_f32_16x16x32_bf16 v[102:105], v[208:211], v[18:21], v[102:105]
	ds_read_b128 v[208:211], v153 offset:17856
	s_waitcnt lgkmcnt(10)
	v_mfma_f32_16x16x32_bf16 v[102:105], v[212:215], v[22:25], v[102:105]
	ds_read_b128 v[212:215], v153 offset:26112
	s_waitcnt lgkmcnt(10)
	v_mfma_f32_16x16x32_bf16 v[102:105], v[216:219], v[26:29], v[102:105]
	ds_read_b128 v[216:219], v153 offset:26176
	s_waitcnt lgkmcnt(10)
	v_mfma_f32_16x16x32_bf16 v[102:105], v[220:223], v[30:33], v[102:105]
	ds_read_b128 v[220:223], v153 offset:26240
	s_waitcnt lgkmcnt(10)
	v_mfma_f32_16x16x32_bf16 v[106:109], v[224:227], v[6:9], 0
	ds_read_b128 v[224:227], v153 offset:26304
	s_waitcnt lgkmcnt(10)
	v_mfma_f32_16x16x32_bf16 v[106:109], v[228:231], v[2:5], v[106:109]
	ds_read_b128 v[228:231], v153 offset:26368
	s_waitcnt lgkmcnt(10)
	v_mfma_f32_16x16x32_bf16 v[106:109], v[232:235], v[10:13], v[106:109]
	ds_read_b128 v[232:235], v153 offset:26432
	s_waitcnt lgkmcnt(10)
	v_mfma_f32_16x16x32_bf16 v[106:109], v[236:239], v[14:17], v[106:109]
	ds_read_b128 v[236:239], v153 offset:26496
	s_waitcnt lgkmcnt(10)
	v_mfma_f32_16x16x32_bf16 v[106:109], v[240:243], v[18:21], v[106:109]
	ds_read_b128 v[240:243], v153 offset:26560
	s_waitcnt lgkmcnt(10)
	v_mfma_f32_16x16x32_bf16 v[106:109], v[244:247], v[22:25], v[106:109]
	ds_read_b64_tr_b16 v[244:245], v152 offset:35008
	ds_read_b64_tr_b16 v[246:247], v152 offset:43712
	s_waitcnt lgkmcnt(11)
	v_mfma_f32_16x16x32_bf16 v[106:109], v[204:207], v[26:29], v[106:109]
	ds_read_b64_tr_b16 v[204:205], v152 offset:35040
	ds_read_b64_tr_b16 v[206:207], v152 offset:43744
	s_waitcnt lgkmcnt(12)
	v_mfma_f32_16x16x32_bf16 v[106:109], v[208:211], v[30:33], v[106:109]
	s_waitcnt lgkmcnt(11)
	s_nop 0
	v_mfma_f32_16x16x32_bf16 v[6:9], v[212:215], v[6:9], 0
	ds_read_b64_tr_b16 v[208:209], v152 offset:35072
	ds_read_b64_tr_b16 v[210:211], v152 offset:43776
	s_waitcnt lgkmcnt(12)
	v_mfma_f32_16x16x32_bf16 v[2:5], v[216:219], v[2:5], v[6:9]
	s_nop 4
	s_waitcnt lgkmcnt(11)
	s_nop 0
	v_mfma_f32_16x16x32_bf16 v[2:5], v[220:223], v[10:13], v[2:5]
	ds_read_b64_tr_b16 v[212:213], v152 offset:35104
	ds_read_b64_tr_b16 v[214:215], v152 offset:43808
	s_waitcnt lgkmcnt(12)
	v_mfma_f32_16x16x32_bf16 v[2:5], v[224:227], v[14:17], v[2:5]
	s_waitcnt lgkmcnt(11)
	s_nop 0
	v_mfma_f32_16x16x32_bf16 v[2:5], v[228:231], v[18:21], v[2:5]
	ds_read_b64_tr_b16 v[216:217], v152 offset:35136
	ds_read_b64_tr_b16 v[218:219], v152 offset:43840
	s_waitcnt lgkmcnt(12)
	v_mfma_f32_16x16x32_bf16 v[2:5], v[232:235], v[22:25], v[2:5]
	s_waitcnt lgkmcnt(11)
	s_nop 0
	v_mfma_f32_16x16x32_bf16 v[2:5], v[236:239], v[26:29], v[2:5]
	ds_read_b64_tr_b16 v[220:221], v152 offset:35168
	ds_read_b64_tr_b16 v[222:223], v152 offset:43872
	s_waitcnt lgkmcnt(12)
	v_mfma_f32_16x16x32_bf16 v[2:5], v[240:243], v[30:33], v[2:5]
	v_mul_f32_e32 v6, 0x3fb8aa3b, v98
	v_mul_f32_e32 v7, 0x3fb8aa3b, v99
	v_max3_f32 v6, v6, s78, v7
	v_mul_f32_e32 v7, 0x3fb8aa3b, v100
	v_mul_f32_e32 v8, 0x3fb8aa3b, v101
	v_max3_f32 v6, v6, v7, v8
	v_mul_f32_e32 v7, 0x3fb8aa3b, v102
	v_mul_f32_e32 v8, 0x3fb8aa3b, v103
	v_max3_f32 v6, v6, v7, v8
	v_mul_f32_e32 v7, 0x3fb8aa3b, v104
	v_mul_f32_e32 v8, 0x3fb8aa3b, v105
	v_max3_f32 v6, v6, v7, v8
	v_mul_f32_e32 v7, 0x3fb8aa3b, v106
	v_mul_f32_e32 v8, 0x3fb8aa3b, v107
	v_max3_f32 v6, v6, v7, v8
	v_mul_f32_e32 v7, 0x3fb8aa3b, v108
	v_mul_f32_e32 v8, 0x3fb8aa3b, v109
	v_max3_f32 v6, v6, v7, v8
	v_mul_f32_e32 v7, 0x3fb8aa3b, v2
	v_mul_f32_e32 v8, 0x3fb8aa3b, v3
	v_max3_f32 v6, v6, v7, v8
	v_mul_f32_e32 v7, 0x3fb8aa3b, v4
	v_mul_f32_e32 v8, 0x3fb8aa3b, v5
	v_max3_f32 v6, v6, v7, v8
	ds_bpermute_b32 v7, v151, v6
	s_waitcnt lgkmcnt(0)
; #define LAS __attribute__((address_space(3)))
; __device__ __forceinline__ void phase_xattn(CArgs& A, int l, unsigned char* lds, int tid) {
;     ...
;             const float mnew = fmaxf(m, mx); const float corr = __builtin_amdgcn_exp2f(m - mnew); m = mnew;
;             float ps = 0.f;
; #pragma unroll
;             for (int blk = 0; blk < 4; ++blk)
; #pragma unroll
;                 for (int e = 0; e < 4; ++e) { sc[blk][e] = __builtin_amdgcn_exp2f(sc[blk][e] - mnew); ps += sc[blk][e]; }
;             lsum = lsum * corr + ps;
; #pragma unroll
;             for (int i = 0; i < 16; ++i) o[i] *= corr;
; #pragma unroll
;             for (int m2 = 0; m2 < 2; ++m2) {
;                 const bf16x8 pb = pack_frag(sc[2 * m2][0], sc[2 * m2][1], sc[2 * m2][2], sc[2 * m2][3], sc[2 * m2 + 1][0], sc[2 * m2 + 1][1], sc[2 * m2 + 1][2], sc[2 * m2 + 1][3]);
; #pragma unroll
;                 for (int db = 0; db < 16; ++db) { const unsigned char* vp = Vt + (32 * m2 + 4 * g + (r >> 2)) * XA_VP + (16 * db + 4 * (r & 3)) * 2;
;                     const s16x4 lo = __builtin_amdgcn_ds_read_tr16_b64_v4i16((LAS s16x4*)vp), hi = __builtin_amdgcn_ds_read_tr16_b64_v4i16((LAS s16x4*)(vp + 16 * XA_VP));
;                     bf16x8 av; av[0] = lo[0]; av[1] = lo[1]; av[2] = lo[2]; av[3] = lo[3]; av[4] = hi[0]; av[5] = hi[1]; av[6] = hi[2]; av[7] = hi[3];
;                     o[db] = __builtin_amdgcn_mfma_f32_16x16x32_bf16(av, pb, o[db], 0, 0, 0); }
	v_max_f32_e32 v7, v7, v7
	v_max_f32_e32 v6, v6, v7
	ds_bpermute_b32 v7, v147, v6
	s_waitcnt lgkmcnt(0)
	v_max3_f32 v6, v156, v6, v7
	v_sub_f32_e32 v7, v156, v6
	v_exp_f32_e32 v110, v7
	v_fma_f32 v7, v98, s83, -v6
	v_exp_f32_e32 v119, v7
	v_fma_f32 v8, v99, s83, -v6
	v_exp_f32_e32 v120, v8
	v_fma_f32 v8, v100, s83, -v6
	v_exp_f32_e32 v121, v8
	v_fma_f32 v8, v101, s83, -v6
	v_exp_f32_e32 v122, v8
	v_fma_f32 v8, v102, s83, -v6
	v_add_f32_e32 v7, 0, v119
	v_exp_f32_e32 v123, v8
	v_fma_f32 v8, v103, s83, -v6
	v_add_f32_e32 v7, v120, v7
	v_exp_f32_e32 v124, v8
	v_fma_f32 v8, v104, s83, -v6
	v_add_f32_e32 v7, v121, v7
	v_exp_f32_e32 v125, v8
	v_fma_f32 v8, v105, s83, -v6
	v_add_f32_e32 v7, v122, v7
	v_exp_f32_e32 v126, v8
	v_fma_f32 v8, v106, s83, -v6
	v_add_f32_e32 v7, v123, v7
	v_exp_f32_e32 v111, v8
	v_fma_f32 v8, v107, s83, -v6
	v_add_f32_e32 v7, v124, v7
	v_exp_f32_e32 v112, v8
	v_fma_f32 v8, v108, s83, -v6
	v_add_f32_e32 v7, v125, v7
	v_exp_f32_e32 v113, v8
	v_fma_f32 v8, v109, s83, -v6
	v_add_f32_e32 v7, v126, v7
	v_exp_f32_e32 v114, v8
	v_fma_f32 v2, v2, s83, -v6
	v_add_f32_e32 v7, v111, v7
	v_exp_f32_e32 v115, v2
	v_fma_f32 v2, v3, s83, -v6
	v_add_f32_e32 v7, v112, v7
	v_exp_f32_e32 v116, v2
	v_fma_f32 v2, v4, s83, -v6
	v_add_f32_e32 v7, v113, v7
	v_exp_f32_e32 v117, v2
	v_fma_f32 v2, v5, s83, -v6
	v_add_f32_e32 v127, v114, v7
	v_exp_f32_e32 v118, v2
	v_pk_mul_f32 v[2:3], v[34:35], v[110:111] op_sel_hi:[1,0]
	v_add_f32_e32 v34, v115, v127
	v_add_f32_e32 v34, v116, v34
	v_add_f32_e32 v34, v117, v34
	v_pk_mul_f32 v[102:103], v[66:67], v[110:111] op_sel_hi:[1,0]
	v_pk_mul_f32 v[66:67], v[82:83], v[110:111] op_sel_hi:[1,0]
	v_pk_mul_f32 v[32:33], v[76:77], v[110:111] op_sel_hi:[1,0]
	v_pk_mul_f32 v[30:31], v[74:75], v[110:111] op_sel_hi:[1,0]
	v_pk_mul_f32 v[28:29], v[60:61], v[110:111] op_sel_hi:[1,0]
	v_pk_mul_f32 v[26:27], v[58:59], v[110:111] op_sel_hi:[1,0]
	v_pk_mul_f32 v[24:25], v[56:57], v[110:111] op_sel_hi:[1,0]
	v_pk_mul_f32 v[22:23], v[54:55], v[110:111] op_sel_hi:[1,0]
	v_pk_mul_f32 v[20:21], v[52:53], v[110:111] op_sel_hi:[1,0]
	v_pk_mul_f32 v[18:19], v[50:51], v[110:111] op_sel_hi:[1,0]
	v_pk_mul_f32 v[16:17], v[48:49], v[110:111] op_sel_hi:[1,0]
	v_pk_mul_f32 v[14:15], v[46:47], v[110:111] op_sel_hi:[1,0]
	v_pk_mul_f32 v[12:13], v[44:45], v[110:111] op_sel_hi:[1,0]
	v_pk_mul_f32 v[10:11], v[42:43], v[110:111] op_sel_hi:[1,0]
	v_pk_mul_f32 v[8:9], v[40:41], v[110:111] op_sel_hi:[1,0]
	v_pk_mul_f32 v[6:7], v[38:39], v[110:111] op_sel_hi:[1,0]
	v_pk_mul_f32 v[4:5], v[36:37], v[110:111] op_sel_hi:[1,0]
	v_add_f32_e32 v82, v118, v34
	v_cvt_pk_bf16_f32 v74, v119, v120
	v_cvt_pk_bf16_f32 v75, v121, v122
	v_cvt_pk_bf16_f32 v76, v123, v124
	v_cvt_pk_bf16_f32 v77, v125, v126
	s_nop 0
	s_nop 0
	s_nop 0
	s_nop 0
	s_nop 0
	s_nop 0
	s_nop 0
	s_nop 0
	s_nop 0
	s_nop 0
	s_nop 0
	s_nop 0
	s_nop 0
	s_nop 0
	v_pk_mul_f32 v[104:105], v[68:69], v[110:111] op_sel_hi:[1,0]
	v_pk_mul_f32 v[68:69], v[84:85], v[110:111] op_sel_hi:[1,0]
	v_pk_mul_f32 v[100:101], v[64:65], v[110:111] op_sel_hi:[1,0]
	v_pk_mul_f32 v[98:99], v[62:63], v[110:111] op_sel_hi:[1,0]
	s_nop 0
	v_mfma_f32_16x16x32_bf16 v[58:61], v[244:247], v[74:77], v[66:69]
	ds_read_b64_tr_b16 v[224:225], v152 offset:35200
	ds_read_b64_tr_b16 v[226:227], v152 offset:43904
	ds_read_b64_tr_b16 v[228:229], v152 offset:35232
	ds_read_b64_tr_b16 v[230:231], v152 offset:43936
	ds_read_b64_tr_b16 v[232:233], v152 offset:35264
	ds_read_b64_tr_b16 v[234:235], v152 offset:43968
	ds_read_b64_tr_b16 v[236:237], v152 offset:34816
	ds_read_b64_tr_b16 v[238:239], v152 offset:43520
	ds_read_b64_tr_b16 v[240:241], v152 offset:34848
	ds_read_b64_tr_b16 v[242:243], v152 offset:43552
	ds_read_b64_tr_b16 v[244:245], v152 offset:34880
	ds_read_b64_tr_b16 v[246:247], v152 offset:43584
	s_nop 2
	s_nop 0
	s_nop 0
	v_pk_mul_f32 v[64:65], v[96:97], v[110:111] op_sel_hi:[1,0]
	v_pk_mul_f32 v[62:63], v[94:95], v[110:111] op_sel_hi:[1,0]
	v_pk_mul_f32 v[108:109], v[88:89], v[110:111] op_sel_hi:[1,0]
	v_pk_mul_f32 v[106:107], v[86:87], v[110:111] op_sel_hi:[1,0]
	s_nop 0
	v_mfma_f32_16x16x32_bf16 v[62:65], v[204:207], v[74:77], v[62:65]
	s_nop 0
	s_nop 0
	v_pk_mul_f32 v[88:89], v[72:73], v[110:111] op_sel_hi:[1,0]
	v_pk_mul_f32 v[86:87], v[70:71], v[110:111] op_sel_hi:[1,0]
	s_nop 0
	v_mfma_f32_16x16x32_bf16 v[30:33], v[208:211], v[74:77], v[30:33]
	s_nop 0
	s_nop 0
	v_pk_mul_f32 v[80:81], v[80:81], v[110:111] op_sel_hi:[1,0]
	v_pk_mul_f32 v[78:79], v[78:79], v[110:111] op_sel_hi:[1,0]
	s_nop 0
	v_mfma_f32_16x16x32_bf16 v[26:29], v[212:215], v[74:77], v[26:29]
	s_nop 0
	s_nop 0
	v_pk_mul_f32 v[72:73], v[92:93], v[110:111] op_sel_hi:[1,0]
	v_pk_mul_f32 v[70:71], v[90:91], v[110:111] op_sel_hi:[1,0]
	s_nop 0
	v_mfma_f32_16x16x32_bf16 v[22:25], v[216:219], v[74:77], v[22:25]
	s_nop 0
	s_nop 0
	v_fmac_f32_e32 v82, v130, v110
	s_nop 0
	v_mfma_f32_16x16x32_bf16 v[18:21], v[220:223], v[74:77], v[18:21]
	s_waitcnt lgkmcnt(10)
	s_nop 0
	s_nop 0
	v_mfma_f32_16x16x32_bf16 v[14:17], v[224:227], v[74:77], v[14:17]
	ds_read_b64_tr_b16 v[204:205], v152 offset:34912
	ds_read_b64_tr_b16 v[206:207], v152 offset:43616
	s_waitcnt lgkmcnt(10)
	v_mfma_f32_16x16x32_bf16 v[10:13], v[228:231], v[74:77], v[10:13]
	ds_read_b64_tr_b16 v[208:209], v152 offset:34944
	ds_read_b64_tr_b16 v[210:211], v152 offset:43648
	s_waitcnt lgkmcnt(10)
	v_mfma_f32_16x16x32_bf16 v[66:69], v[232:235], v[74:77], v[6:9]
	ds_read_b64_tr_b16 v[212:213], v152 offset:34976
	ds_read_b64_tr_b16 v[214:215], v152 offset:43680
	s_nop 2
	s_waitcnt lgkmcnt(10)
	s_nop 0
	v_mfma_f32_16x16x32_bf16 v[34:37], v[236:239], v[74:77], v[106:109]
	ds_read_b64_tr_b16 v[216:217], v152 offset:35296
	ds_read_b64_tr_b16 v[218:219], v152 offset:44000
	s_waitcnt lgkmcnt(10)
; #define LAS __attribute__((address_space(3)))
; __device__ __forceinline__ void phase_xattn(CArgs& A, int l, unsigned char* lds, int tid) {
;     ...
;             for (int m2 = 0; m2 < 2; ++m2) {
;                 const bf16x8 pb = pack_frag(sc[2 * m2][0], sc[2 * m2][1], sc[2 * m2][2], sc[2 * m2][3], sc[2 * m2 + 1][0], sc[2 * m2 + 1][1], sc[2 * m2 + 1][2], sc[2 * m2 + 1][3]);
; #pragma unroll
;                 for (int db = 0; db < 16; ++db) { const unsigned char* vp = Vt + (32 * m2 + 4 * g + (r >> 2)) * XA_VP + (16 * db + 4 * (r & 3)) * 2;
;                     const s16x4 lo = __builtin_amdgcn_ds_read_tr16_b64_v4i16((LAS s16x4*)vp), hi = __builtin_amdgcn_ds_read_tr16_b64_v4i16((LAS s16x4*)(vp + 16 * XA_VP));
;                     bf16x8 av; av[0] = lo[0]; av[1] = lo[1]; av[2] = lo[2]; av[3] = lo[3]; av[4] = hi[0]; av[5] = hi[1]; av[6] = hi[2]; av[7] = hi[3];
;                     o[db] = __builtin_amdgcn_mfma_f32_16x16x32_bf16(av, pb, o[db], 0, 0, 0); }
;             }
;         }
;         float ltot = lsum + __shfl_xor(lsum, 16); ltot += __shfl_xor(ltot, 32);
	v_mfma_f32_16x16x32_bf16 v[38:41], v[240:243], v[74:77], v[102:105]
	ds_read_b64_tr_b16 v[220:221], v152 offset:52224
	ds_read_b64_tr_b16 v[222:223], v152 offset:60928
	s_waitcnt lgkmcnt(10)
	v_mfma_f32_16x16x32_bf16 v[42:45], v[244:247], v[74:77], v[98:101]
	ds_read_b64_tr_b16 v[224:225], v152 offset:52256
	ds_read_b64_tr_b16 v[226:227], v152 offset:60960
	s_waitcnt lgkmcnt(10)
	v_mfma_f32_16x16x32_bf16 v[46:49], v[204:207], v[74:77], v[86:89]
	ds_read_b64_tr_b16 v[228:229], v152 offset:52288
	ds_read_b64_tr_b16 v[230:231], v152 offset:60992
	s_waitcnt lgkmcnt(10)
	v_mfma_f32_16x16x32_bf16 v[50:53], v[208:211], v[74:77], v[78:81]
	ds_read_b64_tr_b16 v[232:233], v152 offset:52320
	ds_read_b64_tr_b16 v[234:235], v152 offset:61024
	s_waitcnt lgkmcnt(10)
	v_mfma_f32_16x16x32_bf16 v[54:57], v[212:215], v[74:77], v[70:73]
	ds_read_b64_tr_b16 v[236:237], v152 offset:52352
	ds_read_b64_tr_b16 v[238:239], v152 offset:61056
	s_waitcnt lgkmcnt(10)
	v_mfma_f32_16x16x32_bf16 v[70:73], v[216:219], v[74:77], v[2:5]
	ds_read_b64_tr_b16 v[240:241], v152 offset:52384
	ds_read_b64_tr_b16 v[242:243], v152 offset:61088
	v_cvt_pk_bf16_f32 v74, v111, v112
	v_cvt_pk_bf16_f32 v75, v113, v114
	v_cvt_pk_bf16_f32 v76, v115, v116
	v_cvt_pk_bf16_f32 v77, v117, v118
	s_nop 2
	s_waitcnt lgkmcnt(10)
	s_nop 0
	s_nop 0
	s_nop 0
	s_nop 0
	v_mfma_f32_16x16x32_bf16 v[2:5], v[220:223], v[74:77], v[34:37]
	ds_read_b64_tr_b16 v[244:245], v152 offset:52416
	ds_read_b64_tr_b16 v[246:247], v152 offset:61120
	s_nop 2
	s_waitcnt lgkmcnt(10)
	s_nop 0
	s_nop 0
	v_mfma_f32_16x16x32_bf16 v[6:9], v[224:227], v[74:77], v[38:41]
	ds_read_b64_tr_b16 v[204:205], v152 offset:52480
	ds_read_b64_tr_b16 v[206:207], v152 offset:61184
	s_nop 2
	s_waitcnt lgkmcnt(10)
	s_nop 0
	s_nop 0
	v_mfma_f32_16x16x32_bf16 v[34:37], v[228:231], v[74:77], v[42:45]
	ds_read_b64_tr_b16 v[208:209], v152 offset:52512
	ds_read_b64_tr_b16 v[210:211], v152 offset:61216
	s_nop 2
	s_waitcnt lgkmcnt(10)
	s_nop 0
	s_nop 0
	v_mfma_f32_16x16x32_bf16 v[38:41], v[232:235], v[74:77], v[46:49]
	ds_read_b64_tr_b16 v[212:213], v152 offset:52544
	ds_read_b64_tr_b16 v[214:215], v152 offset:61248
	s_nop 2
	s_waitcnt lgkmcnt(10)
	s_nop 0
	s_nop 0
	v_mfma_f32_16x16x32_bf16 v[42:45], v[236:239], v[74:77], v[50:53]
	ds_read_b64_tr_b16 v[216:217], v152 offset:52576
	ds_read_b64_tr_b16 v[218:219], v152 offset:61280
	s_nop 2
	s_waitcnt lgkmcnt(10)
	s_nop 0
	s_nop 0
	v_mfma_f32_16x16x32_bf16 v[46:49], v[240:243], v[74:77], v[54:57]
	ds_read_b64_tr_b16 v[220:221], v152 offset:52608
	ds_read_b64_tr_b16 v[222:223], v152 offset:61312
	s_nop 2
	s_waitcnt lgkmcnt(10)
	s_nop 0
	s_nop 0
	v_mfma_f32_16x16x32_bf16 v[50:53], v[244:247], v[74:77], v[58:61]
	ds_read_b64_tr_b16 v[224:225], v152 offset:52640
	ds_read_b64_tr_b16 v[226:227], v152 offset:61344
	s_nop 2
	s_waitcnt lgkmcnt(10)
	s_nop 0
	s_nop 0
	v_mfma_f32_16x16x32_bf16 v[30:33], v[204:207], v[74:77], v[30:33]
	ds_read_b64_tr_b16 v[228:229], v152 offset:52672
	ds_read_b64_tr_b16 v[230:231], v152 offset:61376
	s_waitcnt lgkmcnt(10)
	v_mfma_f32_16x16x32_bf16 v[26:29], v[208:211], v[74:77], v[26:29]
	ds_read_b64_tr_b16 v[232:233], v152 offset:52448
	ds_read_b64_tr_b16 v[234:235], v152 offset:61152
	s_waitcnt lgkmcnt(10)
	v_mfma_f32_16x16x32_bf16 v[22:25], v[212:215], v[74:77], v[22:25]
	ds_read_b64_tr_b16 v[236:237], v152 offset:52704
	ds_read_b64_tr_b16 v[238:239], v152 offset:61408
	s_waitcnt lgkmcnt(10)
	v_mfma_f32_16x16x32_bf16 v[18:21], v[216:219], v[74:77], v[18:21]
	s_waitcnt lgkmcnt(8)
	s_nop 0
	s_nop 0
	v_mfma_f32_16x16x32_bf16 v[14:17], v[220:223], v[74:77], v[14:17]
	s_waitcnt lgkmcnt(6)
	s_nop 0
	s_nop 0
	v_mfma_f32_16x16x32_bf16 v[10:13], v[224:227], v[74:77], v[10:13]
	s_waitcnt lgkmcnt(4)
	s_nop 0
	s_nop 0
	v_mfma_f32_16x16x32_bf16 v[58:61], v[228:231], v[74:77], v[66:69]
	s_nop 2
	ds_bpermute_b32 v66, v151, v82
	s_waitcnt lgkmcnt(0)
	v_add_f32_e32 v66, v82, v66
	ds_bpermute_b32 v67, v147, v66
	v_mfma_f32_16x16x32_bf16 v[54:57], v[232:235], v[74:77], v[62:65]
	s_nop 2
	s_waitcnt lgkmcnt(0)
; __device__ __forceinline__ unsigned cvtpk(float lo, float hi) { unsigned r; asm volatile("v_cvt_pk_bf16_f32 %0, %1, %2" : "=v"(r) : "v"(lo), "v"(hi)); return r; }
; __device__ __forceinline__ void phase_xattn(CArgs& A, int l, unsigned char* lds, int tid) {
;     ...
;         float ltot = lsum + __shfl_xor(lsum, 16); ltot += __shfl_xor(ltot, 32);
;         const float inv = 1.f / ltot;
;         bf16* op = O + row * DM + h * 256 + 4 * g;
; #pragma unroll
;         for (int db = 0; db < 16; ++db) { u32x2 w; w.x = cvtpk(o[db][0] * inv, o[db][1] * inv); w.y = cvtpk(o[db][2] * inv, o[db][3] * inv); *(u32x2*)(op + db * 16) = w; }
;     }
	s_nop 0
	s_nop 0
	v_add_f32_e32 v66, v66, v67
	v_div_scale_f32 v67, s[0:1], v66, v66, 1.0
	v_rcp_f32_e32 v68, v67
	s_nop 0
	v_mfma_f32_16x16x32_bf16 v[62:65], v[236:239], v[74:77], v[70:73]
	v_readlane_b32 s0, v251, 6
	v_readlane_b32 s1, v251, 7
	v_fma_f32 v69, -v67, v68, 1.0
	v_fmac_f32_e32 v68, v69, v68
	v_div_scale_f32 v69, vcc, 1.0, v66, 1.0
	v_mul_f32_e32 v70, v69, v68
	v_fma_f32 v71, -v67, v70, v69
	v_fmac_f32_e32 v70, v71, v68
	v_fma_f32 v67, -v67, v70, v69
	v_div_fmas_f32 v67, v67, v68, v70
	v_div_fixup_f32 v70, v67, v66, 1.0
	v_lshl_add_u64 v[66:67], s[6:7], 0, v[144:145]
	v_mul_f32_e32 v2, v2, v70
	v_mul_f32_e32 v3, v3, v70
	v_lshl_add_u64 v[66:67], v[66:67], 0, s[14:15]
	v_lshlrev_b32_e32 v68, 1, v143
	v_mov_b32_e32 v69, v0
	v_cvt_pk_bf16_f32 v2, v2, v3
	v_mul_f32_e32 v3, v4, v70
	v_lshl_add_u64 v[66:67], v[66:67], 0, v[68:69]
	v_mul_f32_e32 v4, v5, v70
	v_cvt_pk_bf16_f32 v3, v3, v4
	global_store_dwordx2 v[66:67], v[2:3], off
	v_mul_f32_e32 v2, v6, v70
	v_mul_f32_e32 v3, v7, v70
	v_cvt_pk_bf16_f32 v2, v2, v3
	v_mul_f32_e32 v3, v8, v70
	v_mul_f32_e32 v4, v9, v70
	v_cvt_pk_bf16_f32 v3, v3, v4
	global_store_dwordx2 v[66:67], v[2:3], off offset:32
	v_mul_f32_e32 v2, v34, v70
	v_mul_f32_e32 v3, v35, v70
	v_cvt_pk_bf16_f32 v2, v2, v3
	v_mul_f32_e32 v3, v36, v70
	v_mul_f32_e32 v4, v37, v70
	v_cvt_pk_bf16_f32 v3, v3, v4
	global_store_dwordx2 v[66:67], v[2:3], off offset:64
	v_mul_f32_e32 v2, v38, v70
	v_mul_f32_e32 v3, v39, v70
	v_cvt_pk_bf16_f32 v2, v2, v3
	v_mul_f32_e32 v3, v40, v70
	v_mul_f32_e32 v4, v41, v70
	v_cvt_pk_bf16_f32 v3, v3, v4
	global_store_dwordx2 v[66:67], v[2:3], off offset:96
	v_mul_f32_e32 v2, v42, v70
	v_mul_f32_e32 v3, v43, v70
	v_cvt_pk_bf16_f32 v2, v2, v3
	v_mul_f32_e32 v3, v44, v70
	v_mul_f32_e32 v4, v45, v70
	v_cvt_pk_bf16_f32 v3, v3, v4
	global_store_dwordx2 v[66:67], v[2:3], off offset:128
	v_mul_f32_e32 v2, v46, v70
	v_mul_f32_e32 v3, v47, v70
	v_cvt_pk_bf16_f32 v2, v2, v3
	v_mul_f32_e32 v3, v48, v70
	v_mul_f32_e32 v4, v49, v70
	v_cvt_pk_bf16_f32 v3, v3, v4
	global_store_dwordx2 v[66:67], v[2:3], off offset:160
	v_mul_f32_e32 v2, v50, v70
	v_mul_f32_e32 v3, v51, v70
	v_cvt_pk_bf16_f32 v2, v2, v3
	v_mul_f32_e32 v3, v52, v70
	v_mul_f32_e32 v4, v53, v70
	v_cvt_pk_bf16_f32 v3, v3, v4
	global_store_dwordx2 v[66:67], v[2:3], off offset:192
	v_mul_f32_e32 v2, v54, v70
	v_mul_f32_e32 v3, v55, v70
	v_cvt_pk_bf16_f32 v2, v2, v3
	v_mul_f32_e32 v3, v56, v70
	v_mul_f32_e32 v4, v57, v70
	v_cvt_pk_bf16_f32 v3, v3, v4
	global_store_dwordx2 v[66:67], v[2:3], off offset:224
	v_mul_f32_e32 v2, v30, v70
	v_mul_f32_e32 v3, v31, v70
	v_cvt_pk_bf16_f32 v2, v2, v3
	v_mul_f32_e32 v3, v32, v70
	v_mul_f32_e32 v4, v33, v70
	v_cvt_pk_bf16_f32 v3, v3, v4
	global_store_dwordx2 v[66:67], v[2:3], off offset:256
	v_mul_f32_e32 v2, v26, v70
	v_mul_f32_e32 v3, v27, v70
	v_cvt_pk_bf16_f32 v2, v2, v3
	v_mul_f32_e32 v3, v28, v70
	v_mul_f32_e32 v4, v29, v70
	v_cvt_pk_bf16_f32 v3, v3, v4
	global_store_dwordx2 v[66:67], v[2:3], off offset:288
	v_mul_f32_e32 v2, v22, v70
	v_mul_f32_e32 v3, v23, v70
	v_cvt_pk_bf16_f32 v2, v2, v3
	v_mul_f32_e32 v3, v24, v70
	v_mul_f32_e32 v4, v25, v70
	v_cvt_pk_bf16_f32 v3, v3, v4
	global_store_dwordx2 v[66:67], v[2:3], off offset:320
	v_mul_f32_e32 v2, v18, v70
	v_mul_f32_e32 v3, v19, v70
	v_cvt_pk_bf16_f32 v2, v2, v3
	v_mul_f32_e32 v3, v20, v70
	v_mul_f32_e32 v4, v21, v70
	v_cvt_pk_bf16_f32 v3, v3, v4
	global_store_dwordx2 v[66:67], v[2:3], off offset:352
	v_mul_f32_e32 v2, v14, v70
	v_mul_f32_e32 v3, v15, v70
	v_cvt_pk_bf16_f32 v2, v2, v3
	v_mul_f32_e32 v3, v16, v70
	v_mul_f32_e32 v4, v17, v70
	v_cvt_pk_bf16_f32 v3, v3, v4
	global_store_dwordx2 v[66:67], v[2:3], off offset:384
	v_mul_f32_e32 v2, v10, v70
	v_mul_f32_e32 v3, v11, v70
	v_cvt_pk_bf16_f32 v2, v2, v3
	v_mul_f32_e32 v3, v12, v70
	v_mul_f32_e32 v4, v13, v70
	v_cvt_pk_bf16_f32 v3, v3, v4
	global_store_dwordx2 v[66:67], v[2:3], off offset:416
	v_mul_f32_e32 v2, v58, v70
	v_mul_f32_e32 v3, v59, v70
	v_cvt_pk_bf16_f32 v2, v2, v3
	v_mul_f32_e32 v3, v60, v70
	v_mul_f32_e32 v4, v61, v70
	v_cvt_pk_bf16_f32 v3, v3, v4
	global_store_dwordx2 v[66:67], v[2:3], off offset:448
	v_mul_f32_e32 v2, v62, v70
	v_mul_f32_e32 v3, v63, v70
	v_cvt_pk_bf16_f32 v2, v2, v3
	v_mul_f32_e32 v3, v64, v70
	v_mul_f32_e32 v4, v65, v70
	v_cvt_pk_bf16_f32 v3, v3, v4
	global_store_dwordx2 v[66:67], v[2:3], off offset:480
	s_load_dword s0, s[0:1], 0x0
	s_waitcnt lgkmcnt(0)
	s_add_i32 s11, s0, s11
	s_cmpk_gt_i32 s11, 0x3ff
	s_cbranch_scc0 .LBB0_144
